# sc_unit (short-conv mixer) 32-token loop software-pipelined by hand: loads of 8 tokens in flight, DPP reductions; bit-identical numerics
# speedup vs baseline: 1.0137x; 1.0137x over previous
.LBB0_125:
	s_mul_i32 s35, s6, 0x1e00
	s_mul_hi_i32 s31, s6, 0x1e00
	s_add_u32 s38, s26, s35
	s_addc_u32 s39, s27, s31
	s_add_u32 s38, s38, 0x1000
	s_addc_u32 s39, s39, 0
	s_ashr_i32 s3, s6, 31
	s_mov_b32 s2, s6
	s_lshl_b64 s[2:3], s[2:3], 11
	s_add_u32 s2, s74, s2
	s_addc_u32 s3, s75, s3
	global_load_dwordx2 v[36:37], v0, s[38:39] offset:2048
	global_load_dwordx2 v[38:39], v0, s[38:39] offset:2560
	global_load_dwordx2 v[40:41], v0, s[38:39] offset:1536
	s_add_u32 s38, s38, 0x1e00
	s_addc_u32 s39, s39, 0
	global_load_dwordx2 v[42:43], v0, s[38:39] offset:2048
	global_load_dwordx2 v[44:45], v0, s[38:39] offset:2560
	global_load_dwordx2 v[46:47], v0, s[38:39] offset:1536
	s_add_u32 s38, s38, 0x1e00
	s_addc_u32 s39, s39, 0
	global_load_dwordx2 v[48:49], v0, s[38:39] offset:2048
	global_load_dwordx2 v[50:51], v0, s[38:39] offset:2560
	global_load_dwordx2 v[52:53], v0, s[38:39] offset:1536
	s_add_u32 s38, s38, 0x1e00
	s_addc_u32 s39, s39, 0
	global_load_dwordx2 v[54:55], v0, s[38:39] offset:2048
	global_load_dwordx2 v[56:57], v0, s[38:39] offset:2560
	global_load_dwordx2 v[58:59], v0, s[38:39] offset:1536
	s_add_u32 s38, s38, 0x1e00
	s_addc_u32 s39, s39, 0
	global_load_dwordx2 v[60:61], v0, s[38:39] offset:2048
	global_load_dwordx2 v[62:63], v0, s[38:39] offset:2560
	global_load_dwordx2 v[64:65], v0, s[38:39] offset:1536
	s_add_u32 s38, s38, 0x1e00
	s_addc_u32 s39, s39, 0
	global_load_dwordx2 v[66:67], v0, s[38:39] offset:2048
	global_load_dwordx2 v[68:69], v0, s[38:39] offset:2560
	global_load_dwordx2 v[70:71], v0, s[38:39] offset:1536
	s_add_u32 s38, s38, 0x1e00
	s_addc_u32 s39, s39, 0
	global_load_dwordx2 v[72:73], v0, s[38:39] offset:2048
	global_load_dwordx2 v[74:75], v0, s[38:39] offset:2560
	global_load_dwordx2 v[76:77], v0, s[38:39] offset:1536
	s_add_u32 s38, s38, 0x1e00
	s_addc_u32 s39, s39, 0
	global_load_dwordx2 v[78:79], v0, s[38:39] offset:2048
	global_load_dwordx2 v[80:81], v0, s[38:39] offset:2560
	global_load_dwordx2 v[82:83], v0, s[38:39] offset:1536
	s_add_u32 s38, s38, 0x1e00
	s_addc_u32 s39, s39, 0
	global_load_dwordx2 v[84:85], v0, s[38:39] offset:2048
	global_load_dwordx2 v[86:87], v0, s[38:39] offset:2560
	global_load_dwordx2 v[88:89], v0, s[38:39] offset:1536
	s_add_u32 s38, s38, 0x1e00
	s_addc_u32 s39, s39, 0
	global_load_dwordx2 v[90:91], v0, s[38:39] offset:2048
	global_load_dwordx2 v[92:93], v0, s[38:39] offset:2560
	global_load_dwordx2 v[94:95], v0, s[38:39] offset:1536
	s_add_u32 s38, s38, 0x1e00
	s_addc_u32 s39, s39, 0
	global_load_dwordx2 v[96:97], v0, s[38:39] offset:2048
	global_load_dwordx2 v[98:99], v0, s[38:39] offset:2560
	global_load_dwordx2 v[100:101], v0, s[38:39] offset:1536
	s_add_u32 s38, s38, 0x1e00
	s_addc_u32 s39, s39, 0
	global_load_dwordx2 v[102:103], v0, s[38:39] offset:2048
	global_load_dwordx2 v[104:105], v0, s[38:39] offset:2560
	global_load_dwordx2 v[106:107], v0, s[38:39] offset:1536
	s_add_u32 s38, s38, 0x1e00
	s_addc_u32 s39, s39, 0
	global_load_dwordx2 v[108:109], v0, s[38:39] offset:2048
	global_load_dwordx2 v[110:111], v0, s[38:39] offset:2560
	global_load_dwordx2 v[112:113], v0, s[38:39] offset:1536
	s_add_u32 s38, s38, 0x1e00
	s_addc_u32 s39, s39, 0
	global_load_dwordx2 v[114:115], v0, s[38:39] offset:2048
	global_load_dwordx2 v[116:117], v0, s[38:39] offset:2560
	global_load_dwordx2 v[118:119], v0, s[38:39] offset:1536
	s_add_u32 s38, s38, 0x1e00
	s_addc_u32 s39, s39, 0
	global_load_dwordx2 v[120:121], v0, s[38:39] offset:2048
	global_load_dwordx2 v[122:123], v0, s[38:39] offset:2560
	global_load_dwordx2 v[124:125], v0, s[38:39] offset:1536
	s_add_u32 s38, s38, 0x1e00
	s_addc_u32 s39, s39, 0
	global_load_dwordx2 v[126:127], v0, s[38:39] offset:2048
	global_load_dwordx2 v[128:129], v0, s[38:39] offset:2560
	global_load_dwordx2 v[130:131], v0, s[38:39] offset:1536
	s_add_u32 s38, s38, 0x1e00
	s_addc_u32 s39, s39, 0
	s_waitcnt vmcnt(24)
	v_lshlrev_b32_e32 v148, 16, v36
	v_and_b32_e32 v149, 0xffff0000, v36
	v_lshlrev_b32_e32 v150, 16, v38
	v_and_b32_e32 v151, 0xffff0000, v38
	v_lshlrev_b32_e32 v152, 16, v37
	v_and_b32_e32 v153, 0xffff0000, v37
	v_lshlrev_b32_e32 v154, 16, v39
	v_and_b32_e32 v155, 0xffff0000, v39
	v_pk_mul_f32 v[36:37], v[148:149], v[150:151]
	v_pk_mul_f32 v[38:39], v[152:153], v[154:155]
	v_lshlrev_b32_e32 v156, 16, v42
	v_and_b32_e32 v157, 0xffff0000, v42
	v_lshlrev_b32_e32 v158, 16, v44
	v_and_b32_e32 v159, 0xffff0000, v44
	v_lshlrev_b32_e32 v160, 16, v43
	v_and_b32_e32 v161, 0xffff0000, v43
	v_lshlrev_b32_e32 v162, 16, v45
	v_and_b32_e32 v163, 0xffff0000, v45
	v_pk_mul_f32 v[42:43], v[156:157], v[158:159]
	v_pk_mul_f32 v[44:45], v[160:161], v[162:163]
	v_lshlrev_b32_e32 v148, 16, v48
	v_and_b32_e32 v149, 0xffff0000, v48
	v_lshlrev_b32_e32 v150, 16, v50
	v_and_b32_e32 v151, 0xffff0000, v50
	v_lshlrev_b32_e32 v152, 16, v49
	v_and_b32_e32 v153, 0xffff0000, v49
	v_lshlrev_b32_e32 v154, 16, v51
	v_and_b32_e32 v155, 0xffff0000, v51
	v_pk_mul_f32 v[48:49], v[148:149], v[150:151]
	v_pk_mul_f32 v[50:51], v[152:153], v[154:155]
	v_lshlrev_b32_e32 v156, 16, v54
	v_and_b32_e32 v157, 0xffff0000, v54
	v_lshlrev_b32_e32 v158, 16, v56
	v_and_b32_e32 v159, 0xffff0000, v56
	v_lshlrev_b32_e32 v160, 16, v55
	v_and_b32_e32 v161, 0xffff0000, v55
	v_lshlrev_b32_e32 v162, 16, v57
	v_and_b32_e32 v163, 0xffff0000, v57
	v_pk_mul_f32 v[54:55], v[156:157], v[158:159]
	v_pk_mul_f32 v[56:57], v[160:161], v[162:163]
	v_lshlrev_b32_e32 v148, 16, v60
	v_and_b32_e32 v149, 0xffff0000, v60
	v_lshlrev_b32_e32 v150, 16, v62
	v_and_b32_e32 v151, 0xffff0000, v62
	v_lshlrev_b32_e32 v152, 16, v61
	v_and_b32_e32 v153, 0xffff0000, v61
	v_lshlrev_b32_e32 v154, 16, v63
	v_and_b32_e32 v155, 0xffff0000, v63
	v_pk_mul_f32 v[60:61], v[148:149], v[150:151]
	v_pk_mul_f32 v[62:63], v[152:153], v[154:155]
	v_lshlrev_b32_e32 v156, 16, v66
	v_and_b32_e32 v157, 0xffff0000, v66
	v_lshlrev_b32_e32 v158, 16, v68
	v_and_b32_e32 v159, 0xffff0000, v68
	v_lshlrev_b32_e32 v160, 16, v67
	v_and_b32_e32 v161, 0xffff0000, v67
	v_lshlrev_b32_e32 v162, 16, v69
	v_and_b32_e32 v163, 0xffff0000, v69
	v_pk_mul_f32 v[66:67], v[156:157], v[158:159]
	v_pk_mul_f32 v[68:69], v[160:161], v[162:163]
	v_lshlrev_b32_e32 v148, 16, v72
	v_and_b32_e32 v149, 0xffff0000, v72
	v_lshlrev_b32_e32 v150, 16, v74
	v_and_b32_e32 v151, 0xffff0000, v74
	v_lshlrev_b32_e32 v152, 16, v73
	v_and_b32_e32 v153, 0xffff0000, v73
	v_lshlrev_b32_e32 v154, 16, v75
	v_and_b32_e32 v155, 0xffff0000, v75
	v_pk_mul_f32 v[72:73], v[148:149], v[150:151]
	v_pk_mul_f32 v[74:75], v[152:153], v[154:155]
	v_lshlrev_b32_e32 v156, 16, v78
	v_and_b32_e32 v157, 0xffff0000, v78
	v_lshlrev_b32_e32 v158, 16, v80
	v_and_b32_e32 v159, 0xffff0000, v80
	v_lshlrev_b32_e32 v160, 16, v79
	v_and_b32_e32 v161, 0xffff0000, v79
	v_lshlrev_b32_e32 v162, 16, v81
	v_and_b32_e32 v163, 0xffff0000, v81
	v_pk_mul_f32 v[78:79], v[156:157], v[158:159]
	v_pk_mul_f32 v[80:81], v[160:161], v[162:163]
	v_pk_mul_f32 v[152:153], v[6:7], v[22:23]
	v_pk_mul_f32 v[154:155], v[8:9], v[24:25]
	v_pk_fma_f32 v[152:153], v[2:3], v[18:19], v[152:153]
	v_pk_fma_f32 v[154:155], v[4:5], v[20:21], v[154:155]
	v_pk_fma_f32 v[152:153], v[10:11], v[36:37], v[152:153]
	v_pk_fma_f32 v[154:155], v[12:13], v[38:39], v[154:155]
	v_lshlrev_b32_e32 v148, 16, v40
	v_and_b32_e32 v149, 0xffff0000, v40
	v_lshlrev_b32_e32 v150, 16, v41
	v_and_b32_e32 v151, 0xffff0000, v41
	v_pk_mul_f32 v[192:193], v[152:153], v[148:149]
	v_pk_mul_f32 v[194:195], v[154:155], v[150:151]
	v_pk_mul_f32 v[148:149], v[192:193], v[192:193]
	v_pk_mul_f32 v[150:151], v[194:195], v[194:195]
	v_add_f32_e32 v148, v149, v148
	v_add_f32_e32 v150, v150, v151
	v_add_f32_e32 v184, v148, v150
	v_pk_mul_f32 v[160:161], v[6:7], v[36:37]
	v_pk_mul_f32 v[162:163], v[8:9], v[38:39]
	v_pk_fma_f32 v[160:161], v[2:3], v[22:23], v[160:161]
	v_pk_fma_f32 v[162:163], v[4:5], v[24:25], v[162:163]
	v_pk_fma_f32 v[160:161], v[10:11], v[42:43], v[160:161]
	v_pk_fma_f32 v[162:163], v[12:13], v[44:45], v[162:163]
	v_lshlrev_b32_e32 v156, 16, v46
	v_and_b32_e32 v157, 0xffff0000, v46
	v_lshlrev_b32_e32 v158, 16, v47
	v_and_b32_e32 v159, 0xffff0000, v47
	v_pk_mul_f32 v[196:197], v[160:161], v[156:157]
	v_pk_mul_f32 v[198:199], v[162:163], v[158:159]
	v_pk_mul_f32 v[156:157], v[196:197], v[196:197]
	v_pk_mul_f32 v[158:159], v[198:199], v[198:199]
	v_add_f32_e32 v156, v157, v156
	v_add_f32_e32 v158, v158, v159
	v_add_f32_e32 v185, v156, v158
	v_pk_mul_f32 v[152:153], v[6:7], v[42:43]
	v_pk_mul_f32 v[154:155], v[8:9], v[44:45]
	v_pk_fma_f32 v[152:153], v[2:3], v[36:37], v[152:153]
	v_pk_fma_f32 v[154:155], v[4:5], v[38:39], v[154:155]
	v_pk_fma_f32 v[152:153], v[10:11], v[48:49], v[152:153]
	v_pk_fma_f32 v[154:155], v[12:13], v[50:51], v[154:155]
	v_lshlrev_b32_e32 v148, 16, v52
	v_and_b32_e32 v149, 0xffff0000, v52
	v_lshlrev_b32_e32 v150, 16, v53
	v_and_b32_e32 v151, 0xffff0000, v53
	v_pk_mul_f32 v[200:201], v[152:153], v[148:149]
	v_pk_mul_f32 v[202:203], v[154:155], v[150:151]
	v_pk_mul_f32 v[148:149], v[200:201], v[200:201]
	v_pk_mul_f32 v[150:151], v[202:203], v[202:203]
	v_add_f32_e32 v148, v149, v148
	v_add_f32_e32 v150, v150, v151
	v_add_f32_e32 v186, v148, v150
	v_pk_mul_f32 v[160:161], v[6:7], v[48:49]
	v_pk_mul_f32 v[162:163], v[8:9], v[50:51]
	v_pk_fma_f32 v[160:161], v[2:3], v[42:43], v[160:161]
	v_pk_fma_f32 v[162:163], v[4:5], v[44:45], v[162:163]
	v_pk_fma_f32 v[160:161], v[10:11], v[54:55], v[160:161]
	v_pk_fma_f32 v[162:163], v[12:13], v[56:57], v[162:163]
	v_lshlrev_b32_e32 v156, 16, v58
	v_and_b32_e32 v157, 0xffff0000, v58
	v_lshlrev_b32_e32 v158, 16, v59
	v_and_b32_e32 v159, 0xffff0000, v59
	v_pk_mul_f32 v[204:205], v[160:161], v[156:157]
	v_pk_mul_f32 v[206:207], v[162:163], v[158:159]
	v_pk_mul_f32 v[156:157], v[204:205], v[204:205]
	v_pk_mul_f32 v[158:159], v[206:207], v[206:207]
	v_add_f32_e32 v156, v157, v156
	v_add_f32_e32 v158, v158, v159
	v_add_f32_e32 v187, v156, v158
	v_pk_mul_f32 v[152:153], v[6:7], v[54:55]
	v_pk_mul_f32 v[154:155], v[8:9], v[56:57]
	v_pk_fma_f32 v[152:153], v[2:3], v[48:49], v[152:153]
	v_pk_fma_f32 v[154:155], v[4:5], v[50:51], v[154:155]
	v_pk_fma_f32 v[152:153], v[10:11], v[60:61], v[152:153]
	v_pk_fma_f32 v[154:155], v[12:13], v[62:63], v[154:155]
	v_lshlrev_b32_e32 v148, 16, v64
	v_and_b32_e32 v149, 0xffff0000, v64
	v_lshlrev_b32_e32 v150, 16, v65
	v_and_b32_e32 v151, 0xffff0000, v65
	v_pk_mul_f32 v[208:209], v[152:153], v[148:149]
	v_pk_mul_f32 v[210:211], v[154:155], v[150:151]
	v_pk_mul_f32 v[148:149], v[208:209], v[208:209]
	v_pk_mul_f32 v[150:151], v[210:211], v[210:211]
	v_add_f32_e32 v148, v149, v148
	v_add_f32_e32 v150, v150, v151
	v_add_f32_e32 v188, v148, v150
	v_pk_mul_f32 v[160:161], v[6:7], v[60:61]
	v_pk_mul_f32 v[162:163], v[8:9], v[62:63]
	v_pk_fma_f32 v[160:161], v[2:3], v[54:55], v[160:161]
	v_pk_fma_f32 v[162:163], v[4:5], v[56:57], v[162:163]
	v_pk_fma_f32 v[160:161], v[10:11], v[66:67], v[160:161]
	v_pk_fma_f32 v[162:163], v[12:13], v[68:69], v[162:163]
	v_lshlrev_b32_e32 v156, 16, v70
	v_and_b32_e32 v157, 0xffff0000, v70
	v_lshlrev_b32_e32 v158, 16, v71
	v_and_b32_e32 v159, 0xffff0000, v71
	v_pk_mul_f32 v[212:213], v[160:161], v[156:157]
	v_pk_mul_f32 v[214:215], v[162:163], v[158:159]
	v_pk_mul_f32 v[156:157], v[212:213], v[212:213]
	v_pk_mul_f32 v[158:159], v[214:215], v[214:215]
	v_add_f32_e32 v156, v157, v156
	v_add_f32_e32 v158, v158, v159
	v_add_f32_e32 v189, v156, v158
	v_pk_mul_f32 v[152:153], v[6:7], v[66:67]
	v_pk_mul_f32 v[154:155], v[8:9], v[68:69]
	v_pk_fma_f32 v[152:153], v[2:3], v[60:61], v[152:153]
	v_pk_fma_f32 v[154:155], v[4:5], v[62:63], v[154:155]
	v_pk_fma_f32 v[152:153], v[10:11], v[72:73], v[152:153]
	v_pk_fma_f32 v[154:155], v[12:13], v[74:75], v[154:155]
	v_lshlrev_b32_e32 v148, 16, v76
	v_and_b32_e32 v149, 0xffff0000, v76
	v_lshlrev_b32_e32 v150, 16, v77
	v_and_b32_e32 v151, 0xffff0000, v77
	v_pk_mul_f32 v[216:217], v[152:153], v[148:149]
	v_pk_mul_f32 v[218:219], v[154:155], v[150:151]
	v_pk_mul_f32 v[148:149], v[216:217], v[216:217]
	v_pk_mul_f32 v[150:151], v[218:219], v[218:219]
	v_add_f32_e32 v148, v149, v148
	v_add_f32_e32 v150, v150, v151
	v_add_f32_e32 v190, v148, v150
	v_pk_mul_f32 v[160:161], v[6:7], v[72:73]
	v_pk_mul_f32 v[162:163], v[8:9], v[74:75]
	v_pk_fma_f32 v[160:161], v[2:3], v[66:67], v[160:161]
	v_pk_fma_f32 v[162:163], v[4:5], v[68:69], v[162:163]
	v_pk_fma_f32 v[160:161], v[10:11], v[78:79], v[160:161]
	v_pk_fma_f32 v[162:163], v[12:13], v[80:81], v[162:163]
	v_lshlrev_b32_e32 v156, 16, v82
	v_and_b32_e32 v157, 0xffff0000, v82
	v_lshlrev_b32_e32 v158, 16, v83
	v_and_b32_e32 v159, 0xffff0000, v83
	v_pk_mul_f32 v[224:225], v[160:161], v[156:157]
	v_pk_mul_f32 v[226:227], v[162:163], v[158:159]
	v_pk_mul_f32 v[156:157], v[224:225], v[224:225]
	v_pk_mul_f32 v[158:159], v[226:227], v[226:227]
	v_add_f32_e32 v156, v157, v156
	v_add_f32_e32 v158, v158, v159
	v_add_f32_e32 v191, v156, v158
	v_mov_b64_e32 v[18:19], v[72:73]
	v_mov_b64_e32 v[20:21], v[74:75]
	v_mov_b64_e32 v[22:23], v[78:79]
	v_mov_b64_e32 v[24:25], v[80:81]
	v_add_f32_dpp v184, v184, v184 quad_perm:[1,0,3,2] row_mask:0xf bank_mask:0xf
	v_add_f32_dpp v185, v185, v185 quad_perm:[1,0,3,2] row_mask:0xf bank_mask:0xf
	v_add_f32_dpp v186, v186, v186 quad_perm:[1,0,3,2] row_mask:0xf bank_mask:0xf
	v_add_f32_dpp v187, v187, v187 quad_perm:[1,0,3,2] row_mask:0xf bank_mask:0xf
	v_add_f32_dpp v188, v188, v188 quad_perm:[1,0,3,2] row_mask:0xf bank_mask:0xf
	v_add_f32_dpp v189, v189, v189 quad_perm:[1,0,3,2] row_mask:0xf bank_mask:0xf
	v_add_f32_dpp v190, v190, v190 quad_perm:[1,0,3,2] row_mask:0xf bank_mask:0xf
	v_add_f32_dpp v191, v191, v191 quad_perm:[1,0,3,2] row_mask:0xf bank_mask:0xf
	v_add_f32_dpp v184, v184, v184 quad_perm:[2,3,0,1] row_mask:0xf bank_mask:0xf
	v_add_f32_dpp v185, v185, v185 quad_perm:[2,3,0,1] row_mask:0xf bank_mask:0xf
	v_add_f32_dpp v186, v186, v186 quad_perm:[2,3,0,1] row_mask:0xf bank_mask:0xf
	v_add_f32_dpp v187, v187, v187 quad_perm:[2,3,0,1] row_mask:0xf bank_mask:0xf
	v_add_f32_dpp v188, v188, v188 quad_perm:[2,3,0,1] row_mask:0xf bank_mask:0xf
	v_add_f32_dpp v189, v189, v189 quad_perm:[2,3,0,1] row_mask:0xf bank_mask:0xf
	v_add_f32_dpp v190, v190, v190 quad_perm:[2,3,0,1] row_mask:0xf bank_mask:0xf
	v_add_f32_dpp v191, v191, v191 quad_perm:[2,3,0,1] row_mask:0xf bank_mask:0xf
	v_add_f32_dpp v184, v184, v184 row_half_mirror row_mask:0xf bank_mask:0xf
	v_add_f32_dpp v185, v185, v185 row_half_mirror row_mask:0xf bank_mask:0xf
	v_add_f32_dpp v186, v186, v186 row_half_mirror row_mask:0xf bank_mask:0xf
	v_add_f32_dpp v187, v187, v187 row_half_mirror row_mask:0xf bank_mask:0xf
	v_add_f32_dpp v188, v188, v188 row_half_mirror row_mask:0xf bank_mask:0xf
	v_add_f32_dpp v189, v189, v189 row_half_mirror row_mask:0xf bank_mask:0xf
	v_add_f32_dpp v190, v190, v190 row_half_mirror row_mask:0xf bank_mask:0xf
	v_add_f32_dpp v191, v191, v191 row_half_mirror row_mask:0xf bank_mask:0xf
	v_add_f32_dpp v184, v184, v184 row_mirror row_mask:0xf bank_mask:0xf
	v_add_f32_dpp v185, v185, v185 row_mirror row_mask:0xf bank_mask:0xf
	v_add_f32_dpp v186, v186, v186 row_mirror row_mask:0xf bank_mask:0xf
	v_add_f32_dpp v187, v187, v187 row_mirror row_mask:0xf bank_mask:0xf
	v_add_f32_dpp v188, v188, v188 row_mirror row_mask:0xf bank_mask:0xf
	v_add_f32_dpp v189, v189, v189 row_mirror row_mask:0xf bank_mask:0xf
	v_add_f32_dpp v190, v190, v190 row_mirror row_mask:0xf bank_mask:0xf
	v_add_f32_dpp v191, v191, v191 row_mirror row_mask:0xf bank_mask:0xf
	v_fmamk_f32 v184, v184, 0x3c800000, v173
	v_fmamk_f32 v185, v185, 0x3c800000, v173
	v_fmamk_f32 v186, v186, 0x3c800000, v173
	v_fmamk_f32 v187, v187, 0x3c800000, v173
	v_fmamk_f32 v188, v188, 0x3c800000, v173
	v_fmamk_f32 v189, v189, 0x3c800000, v173
	v_fmamk_f32 v190, v190, 0x3c800000, v173
	v_fmamk_f32 v191, v191, 0x3c800000, v173
	v_rsq_f32_e32 v184, v184
	v_rsq_f32_e32 v185, v185
	v_rsq_f32_e32 v186, v186
	v_rsq_f32_e32 v187, v187
	v_rsq_f32_e32 v188, v188
	v_rsq_f32_e32 v189, v189
	v_rsq_f32_e32 v190, v190
	v_rsq_f32_e32 v191, v191
	v_mul_f32_e32 v192, v192, v184
	v_mul_f32_e32 v193, v193, v184
	v_mul_f32_e32 v194, v194, v184
	v_mul_f32_e32 v195, v195, v184
	v_mul_f32_e32 v196, v196, v185
	v_mul_f32_e32 v197, v197, v185
	v_mul_f32_e32 v198, v198, v185
	v_mul_f32_e32 v199, v199, v185
	v_mul_f32_e32 v200, v200, v186
	v_mul_f32_e32 v201, v201, v186
	v_mul_f32_e32 v202, v202, v186
	v_mul_f32_e32 v203, v203, v186
	v_mul_f32_e32 v204, v204, v187
	v_mul_f32_e32 v205, v205, v187
	v_mul_f32_e32 v206, v206, v187
	v_mul_f32_e32 v207, v207, v187
	v_mul_f32_e32 v208, v208, v188
	v_mul_f32_e32 v209, v209, v188
	v_mul_f32_e32 v210, v210, v188
	v_mul_f32_e32 v211, v211, v188
	v_mul_f32_e32 v212, v212, v189
	v_mul_f32_e32 v213, v213, v189
	v_mul_f32_e32 v214, v214, v189
	v_mul_f32_e32 v215, v215, v189
	v_mul_f32_e32 v216, v216, v190
	v_mul_f32_e32 v217, v217, v190
	v_mul_f32_e32 v218, v218, v190
	v_mul_f32_e32 v219, v219, v190
	v_mul_f32_e32 v224, v224, v191
	v_mul_f32_e32 v225, v225, v191
	v_mul_f32_e32 v226, v226, v191
	v_mul_f32_e32 v227, v227, v191
	v_pk_mul_f32 v[192:193], v[14:15], v[192:193]
	v_pk_mul_f32 v[194:195], v[16:17], v[194:195]
	v_pk_mul_f32 v[196:197], v[14:15], v[196:197]
	v_pk_mul_f32 v[198:199], v[16:17], v[198:199]
	v_pk_mul_f32 v[200:201], v[14:15], v[200:201]
	v_pk_mul_f32 v[202:203], v[16:17], v[202:203]
	v_pk_mul_f32 v[204:205], v[14:15], v[204:205]
	v_pk_mul_f32 v[206:207], v[16:17], v[206:207]
	v_pk_mul_f32 v[208:209], v[14:15], v[208:209]
	v_pk_mul_f32 v[210:211], v[16:17], v[210:211]
	v_pk_mul_f32 v[212:213], v[14:15], v[212:213]
	v_pk_mul_f32 v[214:215], v[16:17], v[214:215]
	v_pk_mul_f32 v[216:217], v[14:15], v[216:217]
	v_pk_mul_f32 v[218:219], v[16:17], v[218:219]
	v_pk_mul_f32 v[224:225], v[14:15], v[224:225]
	v_pk_mul_f32 v[226:227], v[16:17], v[226:227]
	v_cvt_pk_bf16_f32 v192, v192, v193
	v_cvt_pk_bf16_f32 v193, v194, v195
	v_cvt_pk_bf16_f32 v196, v196, v197
	v_cvt_pk_bf16_f32 v197, v198, v199
	v_cvt_pk_bf16_f32 v200, v200, v201
	v_cvt_pk_bf16_f32 v201, v202, v203
	v_cvt_pk_bf16_f32 v204, v204, v205
	v_cvt_pk_bf16_f32 v205, v206, v207
	v_cvt_pk_bf16_f32 v208, v208, v209
	v_cvt_pk_bf16_f32 v209, v210, v211
	v_cvt_pk_bf16_f32 v212, v212, v213
	v_cvt_pk_bf16_f32 v213, v214, v215
	v_cvt_pk_bf16_f32 v216, v216, v217
	v_cvt_pk_bf16_f32 v217, v218, v219
	v_cvt_pk_bf16_f32 v224, v224, v225
	v_cvt_pk_bf16_f32 v225, v226, v227
	global_store_dwordx2 v0, v[192:193], s[2:3] offset:1536
	s_add_u32 s2, s2, 0x800
	s_addc_u32 s3, s3, 0
	global_store_dwordx2 v0, v[196:197], s[2:3] offset:1536
	s_add_u32 s2, s2, 0x800
	s_addc_u32 s3, s3, 0
	global_store_dwordx2 v0, v[200:201], s[2:3] offset:1536
	s_add_u32 s2, s2, 0x800
	s_addc_u32 s3, s3, 0
	global_store_dwordx2 v0, v[204:205], s[2:3] offset:1536
	s_add_u32 s2, s2, 0x800
	s_addc_u32 s3, s3, 0
	global_store_dwordx2 v0, v[208:209], s[2:3] offset:1536
	s_add_u32 s2, s2, 0x800
	s_addc_u32 s3, s3, 0
	global_store_dwordx2 v0, v[212:213], s[2:3] offset:1536
	s_add_u32 s2, s2, 0x800
	s_addc_u32 s3, s3, 0
	global_store_dwordx2 v0, v[216:217], s[2:3] offset:1536
	s_add_u32 s2, s2, 0x800
	s_addc_u32 s3, s3, 0
	global_store_dwordx2 v0, v[224:225], s[2:3] offset:1536
	s_add_u32 s2, s2, 0x800
	s_addc_u32 s3, s3, 0
	global_load_dwordx2 v[36:37], v0, s[38:39] offset:2048
	global_load_dwordx2 v[38:39], v0, s[38:39] offset:2560
	global_load_dwordx2 v[40:41], v0, s[38:39] offset:1536
	s_add_u32 s38, s38, 0x1e00
	s_addc_u32 s39, s39, 0
	global_load_dwordx2 v[42:43], v0, s[38:39] offset:2048
	global_load_dwordx2 v[44:45], v0, s[38:39] offset:2560
	global_load_dwordx2 v[46:47], v0, s[38:39] offset:1536
	s_add_u32 s38, s38, 0x1e00
	s_addc_u32 s39, s39, 0
	global_load_dwordx2 v[48:49], v0, s[38:39] offset:2048
	global_load_dwordx2 v[50:51], v0, s[38:39] offset:2560
	global_load_dwordx2 v[52:53], v0, s[38:39] offset:1536
	s_add_u32 s38, s38, 0x1e00
	s_addc_u32 s39, s39, 0
	global_load_dwordx2 v[54:55], v0, s[38:39] offset:2048
	global_load_dwordx2 v[56:57], v0, s[38:39] offset:2560
	global_load_dwordx2 v[58:59], v0, s[38:39] offset:1536
	s_add_u32 s38, s38, 0x1e00
	s_addc_u32 s39, s39, 0
	global_load_dwordx2 v[60:61], v0, s[38:39] offset:2048
	global_load_dwordx2 v[62:63], v0, s[38:39] offset:2560
	global_load_dwordx2 v[64:65], v0, s[38:39] offset:1536
	s_add_u32 s38, s38, 0x1e00
	s_addc_u32 s39, s39, 0
	global_load_dwordx2 v[66:67], v0, s[38:39] offset:2048
	global_load_dwordx2 v[68:69], v0, s[38:39] offset:2560
	global_load_dwordx2 v[70:71], v0, s[38:39] offset:1536
	s_add_u32 s38, s38, 0x1e00
	s_addc_u32 s39, s39, 0
	global_load_dwordx2 v[72:73], v0, s[38:39] offset:2048
	global_load_dwordx2 v[74:75], v0, s[38:39] offset:2560
	global_load_dwordx2 v[76:77], v0, s[38:39] offset:1536
	s_add_u32 s38, s38, 0x1e00
	s_addc_u32 s39, s39, 0
	global_load_dwordx2 v[78:79], v0, s[38:39] offset:2048
	global_load_dwordx2 v[80:81], v0, s[38:39] offset:2560
	global_load_dwordx2 v[82:83], v0, s[38:39] offset:1536
	s_add_u32 s38, s38, 0x1e00
	s_addc_u32 s39, s39, 0
	s_waitcnt vmcnt(32)
	v_lshlrev_b32_e32 v148, 16, v84
	v_and_b32_e32 v149, 0xffff0000, v84
	v_lshlrev_b32_e32 v150, 16, v86
	v_and_b32_e32 v151, 0xffff0000, v86
	v_lshlrev_b32_e32 v152, 16, v85
	v_and_b32_e32 v153, 0xffff0000, v85
	v_lshlrev_b32_e32 v154, 16, v87
	v_and_b32_e32 v155, 0xffff0000, v87
	v_pk_mul_f32 v[84:85], v[148:149], v[150:151]
	v_pk_mul_f32 v[86:87], v[152:153], v[154:155]
	v_lshlrev_b32_e32 v156, 16, v90
	v_and_b32_e32 v157, 0xffff0000, v90
	v_lshlrev_b32_e32 v158, 16, v92
	v_and_b32_e32 v159, 0xffff0000, v92
	v_lshlrev_b32_e32 v160, 16, v91
	v_and_b32_e32 v161, 0xffff0000, v91
	v_lshlrev_b32_e32 v162, 16, v93
	v_and_b32_e32 v163, 0xffff0000, v93
	v_pk_mul_f32 v[90:91], v[156:157], v[158:159]
	v_pk_mul_f32 v[92:93], v[160:161], v[162:163]
	v_lshlrev_b32_e32 v148, 16, v96
	v_and_b32_e32 v149, 0xffff0000, v96
	v_lshlrev_b32_e32 v150, 16, v98
	v_and_b32_e32 v151, 0xffff0000, v98
	v_lshlrev_b32_e32 v152, 16, v97
	v_and_b32_e32 v153, 0xffff0000, v97
	v_lshlrev_b32_e32 v154, 16, v99
	v_and_b32_e32 v155, 0xffff0000, v99
	v_pk_mul_f32 v[96:97], v[148:149], v[150:151]
	v_pk_mul_f32 v[98:99], v[152:153], v[154:155]
	v_lshlrev_b32_e32 v156, 16, v102
	v_and_b32_e32 v157, 0xffff0000, v102
	v_lshlrev_b32_e32 v158, 16, v104
	v_and_b32_e32 v159, 0xffff0000, v104
	v_lshlrev_b32_e32 v160, 16, v103
	v_and_b32_e32 v161, 0xffff0000, v103
	v_lshlrev_b32_e32 v162, 16, v105
	v_and_b32_e32 v163, 0xffff0000, v105
	v_pk_mul_f32 v[102:103], v[156:157], v[158:159]
	v_pk_mul_f32 v[104:105], v[160:161], v[162:163]
	v_lshlrev_b32_e32 v148, 16, v108
	v_and_b32_e32 v149, 0xffff0000, v108
	v_lshlrev_b32_e32 v150, 16, v110
	v_and_b32_e32 v151, 0xffff0000, v110
	v_lshlrev_b32_e32 v152, 16, v109
	v_and_b32_e32 v153, 0xffff0000, v109
	v_lshlrev_b32_e32 v154, 16, v111
	v_and_b32_e32 v155, 0xffff0000, v111
	v_pk_mul_f32 v[108:109], v[148:149], v[150:151]
	v_pk_mul_f32 v[110:111], v[152:153], v[154:155]
	v_lshlrev_b32_e32 v156, 16, v114
	v_and_b32_e32 v157, 0xffff0000, v114
	v_lshlrev_b32_e32 v158, 16, v116
	v_and_b32_e32 v159, 0xffff0000, v116
	v_lshlrev_b32_e32 v160, 16, v115
	v_and_b32_e32 v161, 0xffff0000, v115
	v_lshlrev_b32_e32 v162, 16, v117
	v_and_b32_e32 v163, 0xffff0000, v117
	v_pk_mul_f32 v[114:115], v[156:157], v[158:159]
	v_pk_mul_f32 v[116:117], v[160:161], v[162:163]
	v_lshlrev_b32_e32 v148, 16, v120
	v_and_b32_e32 v149, 0xffff0000, v120
	v_lshlrev_b32_e32 v150, 16, v122
	v_and_b32_e32 v151, 0xffff0000, v122
	v_lshlrev_b32_e32 v152, 16, v121
	v_and_b32_e32 v153, 0xffff0000, v121
	v_lshlrev_b32_e32 v154, 16, v123
	v_and_b32_e32 v155, 0xffff0000, v123
	v_pk_mul_f32 v[120:121], v[148:149], v[150:151]
	v_pk_mul_f32 v[122:123], v[152:153], v[154:155]
	v_lshlrev_b32_e32 v156, 16, v126
	v_and_b32_e32 v157, 0xffff0000, v126
	v_lshlrev_b32_e32 v158, 16, v128
	v_and_b32_e32 v159, 0xffff0000, v128
	v_lshlrev_b32_e32 v160, 16, v127
	v_and_b32_e32 v161, 0xffff0000, v127
	v_lshlrev_b32_e32 v162, 16, v129
	v_and_b32_e32 v163, 0xffff0000, v129
	v_pk_mul_f32 v[126:127], v[156:157], v[158:159]
	v_pk_mul_f32 v[128:129], v[160:161], v[162:163]
	v_pk_mul_f32 v[152:153], v[6:7], v[22:23]
	v_pk_mul_f32 v[154:155], v[8:9], v[24:25]
	v_pk_fma_f32 v[152:153], v[2:3], v[18:19], v[152:153]
	v_pk_fma_f32 v[154:155], v[4:5], v[20:21], v[154:155]
	v_pk_fma_f32 v[152:153], v[10:11], v[84:85], v[152:153]
	v_pk_fma_f32 v[154:155], v[12:13], v[86:87], v[154:155]
	v_lshlrev_b32_e32 v148, 16, v88
	v_and_b32_e32 v149, 0xffff0000, v88
	v_lshlrev_b32_e32 v150, 16, v89
	v_and_b32_e32 v151, 0xffff0000, v89
	v_pk_mul_f32 v[192:193], v[152:153], v[148:149]
	v_pk_mul_f32 v[194:195], v[154:155], v[150:151]
	v_pk_mul_f32 v[148:149], v[192:193], v[192:193]
	v_pk_mul_f32 v[150:151], v[194:195], v[194:195]
	v_add_f32_e32 v148, v149, v148
	v_add_f32_e32 v150, v150, v151
	v_add_f32_e32 v184, v148, v150
	v_pk_mul_f32 v[160:161], v[6:7], v[84:85]
	v_pk_mul_f32 v[162:163], v[8:9], v[86:87]
	v_pk_fma_f32 v[160:161], v[2:3], v[22:23], v[160:161]
	v_pk_fma_f32 v[162:163], v[4:5], v[24:25], v[162:163]
	v_pk_fma_f32 v[160:161], v[10:11], v[90:91], v[160:161]
	v_pk_fma_f32 v[162:163], v[12:13], v[92:93], v[162:163]
	v_lshlrev_b32_e32 v156, 16, v94
	v_and_b32_e32 v157, 0xffff0000, v94
	v_lshlrev_b32_e32 v158, 16, v95
	v_and_b32_e32 v159, 0xffff0000, v95
	v_pk_mul_f32 v[196:197], v[160:161], v[156:157]
	v_pk_mul_f32 v[198:199], v[162:163], v[158:159]
	v_pk_mul_f32 v[156:157], v[196:197], v[196:197]
	v_pk_mul_f32 v[158:159], v[198:199], v[198:199]
	v_add_f32_e32 v156, v157, v156
	v_add_f32_e32 v158, v158, v159
	v_add_f32_e32 v185, v156, v158
	v_pk_mul_f32 v[152:153], v[6:7], v[90:91]
	v_pk_mul_f32 v[154:155], v[8:9], v[92:93]
	v_pk_fma_f32 v[152:153], v[2:3], v[84:85], v[152:153]
	v_pk_fma_f32 v[154:155], v[4:5], v[86:87], v[154:155]
	v_pk_fma_f32 v[152:153], v[10:11], v[96:97], v[152:153]
	v_pk_fma_f32 v[154:155], v[12:13], v[98:99], v[154:155]
	v_lshlrev_b32_e32 v148, 16, v100
	v_and_b32_e32 v149, 0xffff0000, v100
	v_lshlrev_b32_e32 v150, 16, v101
	v_and_b32_e32 v151, 0xffff0000, v101
	v_pk_mul_f32 v[200:201], v[152:153], v[148:149]
	v_pk_mul_f32 v[202:203], v[154:155], v[150:151]
	v_pk_mul_f32 v[148:149], v[200:201], v[200:201]
	v_pk_mul_f32 v[150:151], v[202:203], v[202:203]
	v_add_f32_e32 v148, v149, v148
	v_add_f32_e32 v150, v150, v151
	v_add_f32_e32 v186, v148, v150
	v_pk_mul_f32 v[160:161], v[6:7], v[96:97]
	v_pk_mul_f32 v[162:163], v[8:9], v[98:99]
	v_pk_fma_f32 v[160:161], v[2:3], v[90:91], v[160:161]
	v_pk_fma_f32 v[162:163], v[4:5], v[92:93], v[162:163]
	v_pk_fma_f32 v[160:161], v[10:11], v[102:103], v[160:161]
	v_pk_fma_f32 v[162:163], v[12:13], v[104:105], v[162:163]
	v_lshlrev_b32_e32 v156, 16, v106
	v_and_b32_e32 v157, 0xffff0000, v106
	v_lshlrev_b32_e32 v158, 16, v107
	v_and_b32_e32 v159, 0xffff0000, v107
	v_pk_mul_f32 v[204:205], v[160:161], v[156:157]
	v_pk_mul_f32 v[206:207], v[162:163], v[158:159]
	v_pk_mul_f32 v[156:157], v[204:205], v[204:205]
	v_pk_mul_f32 v[158:159], v[206:207], v[206:207]
	v_add_f32_e32 v156, v157, v156
	v_add_f32_e32 v158, v158, v159
	v_add_f32_e32 v187, v156, v158
	v_pk_mul_f32 v[152:153], v[6:7], v[102:103]
	v_pk_mul_f32 v[154:155], v[8:9], v[104:105]
	v_pk_fma_f32 v[152:153], v[2:3], v[96:97], v[152:153]
	v_pk_fma_f32 v[154:155], v[4:5], v[98:99], v[154:155]
	v_pk_fma_f32 v[152:153], v[10:11], v[108:109], v[152:153]
	v_pk_fma_f32 v[154:155], v[12:13], v[110:111], v[154:155]
	v_lshlrev_b32_e32 v148, 16, v112
	v_and_b32_e32 v149, 0xffff0000, v112
	v_lshlrev_b32_e32 v150, 16, v113
	v_and_b32_e32 v151, 0xffff0000, v113
	v_pk_mul_f32 v[208:209], v[152:153], v[148:149]
	v_pk_mul_f32 v[210:211], v[154:155], v[150:151]
	v_pk_mul_f32 v[148:149], v[208:209], v[208:209]
	v_pk_mul_f32 v[150:151], v[210:211], v[210:211]
	v_add_f32_e32 v148, v149, v148
	v_add_f32_e32 v150, v150, v151
	v_add_f32_e32 v188, v148, v150
	v_pk_mul_f32 v[160:161], v[6:7], v[108:109]
	v_pk_mul_f32 v[162:163], v[8:9], v[110:111]
	v_pk_fma_f32 v[160:161], v[2:3], v[102:103], v[160:161]
	v_pk_fma_f32 v[162:163], v[4:5], v[104:105], v[162:163]
	v_pk_fma_f32 v[160:161], v[10:11], v[114:115], v[160:161]
	v_pk_fma_f32 v[162:163], v[12:13], v[116:117], v[162:163]
	v_lshlrev_b32_e32 v156, 16, v118
	v_and_b32_e32 v157, 0xffff0000, v118
	v_lshlrev_b32_e32 v158, 16, v119
	v_and_b32_e32 v159, 0xffff0000, v119
	v_pk_mul_f32 v[212:213], v[160:161], v[156:157]
	v_pk_mul_f32 v[214:215], v[162:163], v[158:159]
	v_pk_mul_f32 v[156:157], v[212:213], v[212:213]
	v_pk_mul_f32 v[158:159], v[214:215], v[214:215]
	v_add_f32_e32 v156, v157, v156
	v_add_f32_e32 v158, v158, v159
	v_add_f32_e32 v189, v156, v158
	v_pk_mul_f32 v[152:153], v[6:7], v[114:115]
	v_pk_mul_f32 v[154:155], v[8:9], v[116:117]
	v_pk_fma_f32 v[152:153], v[2:3], v[108:109], v[152:153]
	v_pk_fma_f32 v[154:155], v[4:5], v[110:111], v[154:155]
	v_pk_fma_f32 v[152:153], v[10:11], v[120:121], v[152:153]
	v_pk_fma_f32 v[154:155], v[12:13], v[122:123], v[154:155]
	v_lshlrev_b32_e32 v148, 16, v124
	v_and_b32_e32 v149, 0xffff0000, v124
	v_lshlrev_b32_e32 v150, 16, v125
	v_and_b32_e32 v151, 0xffff0000, v125
	v_pk_mul_f32 v[216:217], v[152:153], v[148:149]
	v_pk_mul_f32 v[218:219], v[154:155], v[150:151]
	v_pk_mul_f32 v[148:149], v[216:217], v[216:217]
	v_pk_mul_f32 v[150:151], v[218:219], v[218:219]
	v_add_f32_e32 v148, v149, v148
	v_add_f32_e32 v150, v150, v151
	v_add_f32_e32 v190, v148, v150
	v_pk_mul_f32 v[160:161], v[6:7], v[120:121]
	v_pk_mul_f32 v[162:163], v[8:9], v[122:123]
	v_pk_fma_f32 v[160:161], v[2:3], v[114:115], v[160:161]
	v_pk_fma_f32 v[162:163], v[4:5], v[116:117], v[162:163]
	v_pk_fma_f32 v[160:161], v[10:11], v[126:127], v[160:161]
	v_pk_fma_f32 v[162:163], v[12:13], v[128:129], v[162:163]
	v_lshlrev_b32_e32 v156, 16, v130
	v_and_b32_e32 v157, 0xffff0000, v130
	v_lshlrev_b32_e32 v158, 16, v131
	v_and_b32_e32 v159, 0xffff0000, v131
	v_pk_mul_f32 v[224:225], v[160:161], v[156:157]
	v_pk_mul_f32 v[226:227], v[162:163], v[158:159]
	v_pk_mul_f32 v[156:157], v[224:225], v[224:225]
	v_pk_mul_f32 v[158:159], v[226:227], v[226:227]
	v_add_f32_e32 v156, v157, v156
	v_add_f32_e32 v158, v158, v159
	v_add_f32_e32 v191, v156, v158
	v_mov_b64_e32 v[18:19], v[120:121]
	v_mov_b64_e32 v[20:21], v[122:123]
	v_mov_b64_e32 v[22:23], v[126:127]
	v_mov_b64_e32 v[24:25], v[128:129]
	v_add_f32_dpp v184, v184, v184 quad_perm:[1,0,3,2] row_mask:0xf bank_mask:0xf
	v_add_f32_dpp v185, v185, v185 quad_perm:[1,0,3,2] row_mask:0xf bank_mask:0xf
	v_add_f32_dpp v186, v186, v186 quad_perm:[1,0,3,2] row_mask:0xf bank_mask:0xf
	v_add_f32_dpp v187, v187, v187 quad_perm:[1,0,3,2] row_mask:0xf bank_mask:0xf
	v_add_f32_dpp v188, v188, v188 quad_perm:[1,0,3,2] row_mask:0xf bank_mask:0xf
	v_add_f32_dpp v189, v189, v189 quad_perm:[1,0,3,2] row_mask:0xf bank_mask:0xf
	v_add_f32_dpp v190, v190, v190 quad_perm:[1,0,3,2] row_mask:0xf bank_mask:0xf
	v_add_f32_dpp v191, v191, v191 quad_perm:[1,0,3,2] row_mask:0xf bank_mask:0xf
	v_add_f32_dpp v184, v184, v184 quad_perm:[2,3,0,1] row_mask:0xf bank_mask:0xf
	v_add_f32_dpp v185, v185, v185 quad_perm:[2,3,0,1] row_mask:0xf bank_mask:0xf
	v_add_f32_dpp v186, v186, v186 quad_perm:[2,3,0,1] row_mask:0xf bank_mask:0xf
	v_add_f32_dpp v187, v187, v187 quad_perm:[2,3,0,1] row_mask:0xf bank_mask:0xf
	v_add_f32_dpp v188, v188, v188 quad_perm:[2,3,0,1] row_mask:0xf bank_mask:0xf
	v_add_f32_dpp v189, v189, v189 quad_perm:[2,3,0,1] row_mask:0xf bank_mask:0xf
	v_add_f32_dpp v190, v190, v190 quad_perm:[2,3,0,1] row_mask:0xf bank_mask:0xf
	v_add_f32_dpp v191, v191, v191 quad_perm:[2,3,0,1] row_mask:0xf bank_mask:0xf
	v_add_f32_dpp v184, v184, v184 row_half_mirror row_mask:0xf bank_mask:0xf
	v_add_f32_dpp v185, v185, v185 row_half_mirror row_mask:0xf bank_mask:0xf
	v_add_f32_dpp v186, v186, v186 row_half_mirror row_mask:0xf bank_mask:0xf
	v_add_f32_dpp v187, v187, v187 row_half_mirror row_mask:0xf bank_mask:0xf
	v_add_f32_dpp v188, v188, v188 row_half_mirror row_mask:0xf bank_mask:0xf
	v_add_f32_dpp v189, v189, v189 row_half_mirror row_mask:0xf bank_mask:0xf
	v_add_f32_dpp v190, v190, v190 row_half_mirror row_mask:0xf bank_mask:0xf
	v_add_f32_dpp v191, v191, v191 row_half_mirror row_mask:0xf bank_mask:0xf
	v_add_f32_dpp v184, v184, v184 row_mirror row_mask:0xf bank_mask:0xf
	v_add_f32_dpp v185, v185, v185 row_mirror row_mask:0xf bank_mask:0xf
	v_add_f32_dpp v186, v186, v186 row_mirror row_mask:0xf bank_mask:0xf
	v_add_f32_dpp v187, v187, v187 row_mirror row_mask:0xf bank_mask:0xf
	v_add_f32_dpp v188, v188, v188 row_mirror row_mask:0xf bank_mask:0xf
	v_add_f32_dpp v189, v189, v189 row_mirror row_mask:0xf bank_mask:0xf
	v_add_f32_dpp v190, v190, v190 row_mirror row_mask:0xf bank_mask:0xf
	v_add_f32_dpp v191, v191, v191 row_mirror row_mask:0xf bank_mask:0xf
	v_fmamk_f32 v184, v184, 0x3c800000, v173
	v_fmamk_f32 v185, v185, 0x3c800000, v173
	v_fmamk_f32 v186, v186, 0x3c800000, v173
	v_fmamk_f32 v187, v187, 0x3c800000, v173
	v_fmamk_f32 v188, v188, 0x3c800000, v173
	v_fmamk_f32 v189, v189, 0x3c800000, v173
	v_fmamk_f32 v190, v190, 0x3c800000, v173
	v_fmamk_f32 v191, v191, 0x3c800000, v173
	v_rsq_f32_e32 v184, v184
	v_rsq_f32_e32 v185, v185
	v_rsq_f32_e32 v186, v186
	v_rsq_f32_e32 v187, v187
	v_rsq_f32_e32 v188, v188
	v_rsq_f32_e32 v189, v189
	v_rsq_f32_e32 v190, v190
	v_rsq_f32_e32 v191, v191
	v_mul_f32_e32 v192, v192, v184
	v_mul_f32_e32 v193, v193, v184
	v_mul_f32_e32 v194, v194, v184
	v_mul_f32_e32 v195, v195, v184
	v_mul_f32_e32 v196, v196, v185
	v_mul_f32_e32 v197, v197, v185
	v_mul_f32_e32 v198, v198, v185
	v_mul_f32_e32 v199, v199, v185
	v_mul_f32_e32 v200, v200, v186
	v_mul_f32_e32 v201, v201, v186
	v_mul_f32_e32 v202, v202, v186
	v_mul_f32_e32 v203, v203, v186
	v_mul_f32_e32 v204, v204, v187
	v_mul_f32_e32 v205, v205, v187
	v_mul_f32_e32 v206, v206, v187
	v_mul_f32_e32 v207, v207, v187
	v_mul_f32_e32 v208, v208, v188
	v_mul_f32_e32 v209, v209, v188
	v_mul_f32_e32 v210, v210, v188
	v_mul_f32_e32 v211, v211, v188
	v_mul_f32_e32 v212, v212, v189
	v_mul_f32_e32 v213, v213, v189
	v_mul_f32_e32 v214, v214, v189
	v_mul_f32_e32 v215, v215, v189
	v_mul_f32_e32 v216, v216, v190
	v_mul_f32_e32 v217, v217, v190
	v_mul_f32_e32 v218, v218, v190
	v_mul_f32_e32 v219, v219, v190
	v_mul_f32_e32 v224, v224, v191
	v_mul_f32_e32 v225, v225, v191
	v_mul_f32_e32 v226, v226, v191
	v_mul_f32_e32 v227, v227, v191
	v_pk_mul_f32 v[192:193], v[14:15], v[192:193]
	v_pk_mul_f32 v[194:195], v[16:17], v[194:195]
	v_pk_mul_f32 v[196:197], v[14:15], v[196:197]
	v_pk_mul_f32 v[198:199], v[16:17], v[198:199]
	v_pk_mul_f32 v[200:201], v[14:15], v[200:201]
	v_pk_mul_f32 v[202:203], v[16:17], v[202:203]
	v_pk_mul_f32 v[204:205], v[14:15], v[204:205]
	v_pk_mul_f32 v[206:207], v[16:17], v[206:207]
	v_pk_mul_f32 v[208:209], v[14:15], v[208:209]
	v_pk_mul_f32 v[210:211], v[16:17], v[210:211]
	v_pk_mul_f32 v[212:213], v[14:15], v[212:213]
	v_pk_mul_f32 v[214:215], v[16:17], v[214:215]
	v_pk_mul_f32 v[216:217], v[14:15], v[216:217]
	v_pk_mul_f32 v[218:219], v[16:17], v[218:219]
	v_pk_mul_f32 v[224:225], v[14:15], v[224:225]
	v_pk_mul_f32 v[226:227], v[16:17], v[226:227]
	v_cvt_pk_bf16_f32 v192, v192, v193
	v_cvt_pk_bf16_f32 v193, v194, v195
	v_cvt_pk_bf16_f32 v196, v196, v197
	v_cvt_pk_bf16_f32 v197, v198, v199
	v_cvt_pk_bf16_f32 v200, v200, v201
	v_cvt_pk_bf16_f32 v201, v202, v203
	v_cvt_pk_bf16_f32 v204, v204, v205
	v_cvt_pk_bf16_f32 v205, v206, v207
	v_cvt_pk_bf16_f32 v208, v208, v209
	v_cvt_pk_bf16_f32 v209, v210, v211
	v_cvt_pk_bf16_f32 v212, v212, v213
	v_cvt_pk_bf16_f32 v213, v214, v215
	v_cvt_pk_bf16_f32 v216, v216, v217
	v_cvt_pk_bf16_f32 v217, v218, v219
	v_cvt_pk_bf16_f32 v224, v224, v225
	v_cvt_pk_bf16_f32 v225, v226, v227
	global_store_dwordx2 v0, v[192:193], s[2:3] offset:1536
	s_add_u32 s2, s2, 0x800
	s_addc_u32 s3, s3, 0
	global_store_dwordx2 v0, v[196:197], s[2:3] offset:1536
	s_add_u32 s2, s2, 0x800
	s_addc_u32 s3, s3, 0
	global_store_dwordx2 v0, v[200:201], s[2:3] offset:1536
	s_add_u32 s2, s2, 0x800
	s_addc_u32 s3, s3, 0
	global_store_dwordx2 v0, v[204:205], s[2:3] offset:1536
	s_add_u32 s2, s2, 0x800
	s_addc_u32 s3, s3, 0
	global_store_dwordx2 v0, v[208:209], s[2:3] offset:1536
	s_add_u32 s2, s2, 0x800
	s_addc_u32 s3, s3, 0
	global_store_dwordx2 v0, v[212:213], s[2:3] offset:1536
	s_add_u32 s2, s2, 0x800
	s_addc_u32 s3, s3, 0
	global_store_dwordx2 v0, v[216:217], s[2:3] offset:1536
	s_add_u32 s2, s2, 0x800
	s_addc_u32 s3, s3, 0
	global_store_dwordx2 v0, v[224:225], s[2:3] offset:1536
	s_add_u32 s2, s2, 0x800
	s_addc_u32 s3, s3, 0
	global_load_dwordx2 v[84:85], v0, s[38:39] offset:2048
	global_load_dwordx2 v[86:87], v0, s[38:39] offset:2560
	global_load_dwordx2 v[88:89], v0, s[38:39] offset:1536
	s_add_u32 s38, s38, 0x1e00
	s_addc_u32 s39, s39, 0
	global_load_dwordx2 v[90:91], v0, s[38:39] offset:2048
	global_load_dwordx2 v[92:93], v0, s[38:39] offset:2560
	global_load_dwordx2 v[94:95], v0, s[38:39] offset:1536
	s_add_u32 s38, s38, 0x1e00
	s_addc_u32 s39, s39, 0
	global_load_dwordx2 v[96:97], v0, s[38:39] offset:2048
	global_load_dwordx2 v[98:99], v0, s[38:39] offset:2560
	global_load_dwordx2 v[100:101], v0, s[38:39] offset:1536
	s_add_u32 s38, s38, 0x1e00
	s_addc_u32 s39, s39, 0
	global_load_dwordx2 v[102:103], v0, s[38:39] offset:2048
	global_load_dwordx2 v[104:105], v0, s[38:39] offset:2560
	global_load_dwordx2 v[106:107], v0, s[38:39] offset:1536
	s_add_u32 s38, s38, 0x1e00
	s_addc_u32 s39, s39, 0
	global_load_dwordx2 v[108:109], v0, s[38:39] offset:2048
	global_load_dwordx2 v[110:111], v0, s[38:39] offset:2560
	global_load_dwordx2 v[112:113], v0, s[38:39] offset:1536
	s_add_u32 s38, s38, 0x1e00
	s_addc_u32 s39, s39, 0
	global_load_dwordx2 v[114:115], v0, s[38:39] offset:2048
	global_load_dwordx2 v[116:117], v0, s[38:39] offset:2560
	global_load_dwordx2 v[118:119], v0, s[38:39] offset:1536
	s_add_u32 s38, s38, 0x1e00
	s_addc_u32 s39, s39, 0
	global_load_dwordx2 v[120:121], v0, s[38:39] offset:2048
	global_load_dwordx2 v[122:123], v0, s[38:39] offset:2560
	global_load_dwordx2 v[124:125], v0, s[38:39] offset:1536
	s_add_u32 s38, s38, 0x1e00
	s_addc_u32 s39, s39, 0
	global_load_dwordx2 v[126:127], v0, s[38:39] offset:2048
	global_load_dwordx2 v[128:129], v0, s[38:39] offset:2560
	global_load_dwordx2 v[130:131], v0, s[38:39] offset:1536
	s_add_u32 s38, s38, 0x1e00
	s_addc_u32 s39, s39, 0
	s_waitcnt vmcnt(32)
	v_lshlrev_b32_e32 v148, 16, v36
	v_and_b32_e32 v149, 0xffff0000, v36
	v_lshlrev_b32_e32 v150, 16, v38
	v_and_b32_e32 v151, 0xffff0000, v38
	v_lshlrev_b32_e32 v152, 16, v37
	v_and_b32_e32 v153, 0xffff0000, v37
	v_lshlrev_b32_e32 v154, 16, v39
	v_and_b32_e32 v155, 0xffff0000, v39
	v_pk_mul_f32 v[36:37], v[148:149], v[150:151]
	v_pk_mul_f32 v[38:39], v[152:153], v[154:155]
	v_lshlrev_b32_e32 v156, 16, v42
	v_and_b32_e32 v157, 0xffff0000, v42
	v_lshlrev_b32_e32 v158, 16, v44
	v_and_b32_e32 v159, 0xffff0000, v44
	v_lshlrev_b32_e32 v160, 16, v43
	v_and_b32_e32 v161, 0xffff0000, v43
	v_lshlrev_b32_e32 v162, 16, v45
	v_and_b32_e32 v163, 0xffff0000, v45
	v_pk_mul_f32 v[42:43], v[156:157], v[158:159]
	v_pk_mul_f32 v[44:45], v[160:161], v[162:163]
	v_lshlrev_b32_e32 v148, 16, v48
	v_and_b32_e32 v149, 0xffff0000, v48
	v_lshlrev_b32_e32 v150, 16, v50
	v_and_b32_e32 v151, 0xffff0000, v50
	v_lshlrev_b32_e32 v152, 16, v49
	v_and_b32_e32 v153, 0xffff0000, v49
	v_lshlrev_b32_e32 v154, 16, v51
	v_and_b32_e32 v155, 0xffff0000, v51
	v_pk_mul_f32 v[48:49], v[148:149], v[150:151]
	v_pk_mul_f32 v[50:51], v[152:153], v[154:155]
	v_lshlrev_b32_e32 v156, 16, v54
	v_and_b32_e32 v157, 0xffff0000, v54
	v_lshlrev_b32_e32 v158, 16, v56
	v_and_b32_e32 v159, 0xffff0000, v56
	v_lshlrev_b32_e32 v160, 16, v55
	v_and_b32_e32 v161, 0xffff0000, v55
	v_lshlrev_b32_e32 v162, 16, v57
	v_and_b32_e32 v163, 0xffff0000, v57
	v_pk_mul_f32 v[54:55], v[156:157], v[158:159]
	v_pk_mul_f32 v[56:57], v[160:161], v[162:163]
	v_lshlrev_b32_e32 v148, 16, v60
	v_and_b32_e32 v149, 0xffff0000, v60
	v_lshlrev_b32_e32 v150, 16, v62
	v_and_b32_e32 v151, 0xffff0000, v62
	v_lshlrev_b32_e32 v152, 16, v61
	v_and_b32_e32 v153, 0xffff0000, v61
	v_lshlrev_b32_e32 v154, 16, v63
	v_and_b32_e32 v155, 0xffff0000, v63
	v_pk_mul_f32 v[60:61], v[148:149], v[150:151]
	v_pk_mul_f32 v[62:63], v[152:153], v[154:155]
	v_lshlrev_b32_e32 v156, 16, v66
	v_and_b32_e32 v157, 0xffff0000, v66
	v_lshlrev_b32_e32 v158, 16, v68
	v_and_b32_e32 v159, 0xffff0000, v68
	v_lshlrev_b32_e32 v160, 16, v67
	v_and_b32_e32 v161, 0xffff0000, v67
	v_lshlrev_b32_e32 v162, 16, v69
	v_and_b32_e32 v163, 0xffff0000, v69
	v_pk_mul_f32 v[66:67], v[156:157], v[158:159]
	v_pk_mul_f32 v[68:69], v[160:161], v[162:163]
	v_lshlrev_b32_e32 v148, 16, v72
	v_and_b32_e32 v149, 0xffff0000, v72
	v_lshlrev_b32_e32 v150, 16, v74
	v_and_b32_e32 v151, 0xffff0000, v74
	v_lshlrev_b32_e32 v152, 16, v73
	v_and_b32_e32 v153, 0xffff0000, v73
	v_lshlrev_b32_e32 v154, 16, v75
	v_and_b32_e32 v155, 0xffff0000, v75
	v_pk_mul_f32 v[72:73], v[148:149], v[150:151]
	v_pk_mul_f32 v[74:75], v[152:153], v[154:155]
	v_lshlrev_b32_e32 v156, 16, v78
	v_and_b32_e32 v157, 0xffff0000, v78
	v_lshlrev_b32_e32 v158, 16, v80
	v_and_b32_e32 v159, 0xffff0000, v80
	v_lshlrev_b32_e32 v160, 16, v79
	v_and_b32_e32 v161, 0xffff0000, v79
	v_lshlrev_b32_e32 v162, 16, v81
	v_and_b32_e32 v163, 0xffff0000, v81
	v_pk_mul_f32 v[78:79], v[156:157], v[158:159]
	v_pk_mul_f32 v[80:81], v[160:161], v[162:163]
	v_pk_mul_f32 v[152:153], v[6:7], v[22:23]
	v_pk_mul_f32 v[154:155], v[8:9], v[24:25]
	v_pk_fma_f32 v[152:153], v[2:3], v[18:19], v[152:153]
	v_pk_fma_f32 v[154:155], v[4:5], v[20:21], v[154:155]
	v_pk_fma_f32 v[152:153], v[10:11], v[36:37], v[152:153]
	v_pk_fma_f32 v[154:155], v[12:13], v[38:39], v[154:155]
	v_lshlrev_b32_e32 v148, 16, v40
	v_and_b32_e32 v149, 0xffff0000, v40
	v_lshlrev_b32_e32 v150, 16, v41
	v_and_b32_e32 v151, 0xffff0000, v41
	v_pk_mul_f32 v[192:193], v[152:153], v[148:149]
	v_pk_mul_f32 v[194:195], v[154:155], v[150:151]
	v_pk_mul_f32 v[148:149], v[192:193], v[192:193]
	v_pk_mul_f32 v[150:151], v[194:195], v[194:195]
	v_add_f32_e32 v148, v149, v148
	v_add_f32_e32 v150, v150, v151
	v_add_f32_e32 v184, v148, v150
	v_pk_mul_f32 v[160:161], v[6:7], v[36:37]
	v_pk_mul_f32 v[162:163], v[8:9], v[38:39]
	v_pk_fma_f32 v[160:161], v[2:3], v[22:23], v[160:161]
	v_pk_fma_f32 v[162:163], v[4:5], v[24:25], v[162:163]
	v_pk_fma_f32 v[160:161], v[10:11], v[42:43], v[160:161]
	v_pk_fma_f32 v[162:163], v[12:13], v[44:45], v[162:163]
	v_lshlrev_b32_e32 v156, 16, v46
	v_and_b32_e32 v157, 0xffff0000, v46
	v_lshlrev_b32_e32 v158, 16, v47
	v_and_b32_e32 v159, 0xffff0000, v47
	v_pk_mul_f32 v[196:197], v[160:161], v[156:157]
	v_pk_mul_f32 v[198:199], v[162:163], v[158:159]
	v_pk_mul_f32 v[156:157], v[196:197], v[196:197]
	v_pk_mul_f32 v[158:159], v[198:199], v[198:199]
	v_add_f32_e32 v156, v157, v156
	v_add_f32_e32 v158, v158, v159
	v_add_f32_e32 v185, v156, v158
	v_pk_mul_f32 v[152:153], v[6:7], v[42:43]
	v_pk_mul_f32 v[154:155], v[8:9], v[44:45]
	v_pk_fma_f32 v[152:153], v[2:3], v[36:37], v[152:153]
	v_pk_fma_f32 v[154:155], v[4:5], v[38:39], v[154:155]
	v_pk_fma_f32 v[152:153], v[10:11], v[48:49], v[152:153]
	v_pk_fma_f32 v[154:155], v[12:13], v[50:51], v[154:155]
	v_lshlrev_b32_e32 v148, 16, v52
	v_and_b32_e32 v149, 0xffff0000, v52
	v_lshlrev_b32_e32 v150, 16, v53
	v_and_b32_e32 v151, 0xffff0000, v53
	v_pk_mul_f32 v[200:201], v[152:153], v[148:149]
	v_pk_mul_f32 v[202:203], v[154:155], v[150:151]
	v_pk_mul_f32 v[148:149], v[200:201], v[200:201]
	v_pk_mul_f32 v[150:151], v[202:203], v[202:203]
	v_add_f32_e32 v148, v149, v148
	v_add_f32_e32 v150, v150, v151
	v_add_f32_e32 v186, v148, v150
	v_pk_mul_f32 v[160:161], v[6:7], v[48:49]
	v_pk_mul_f32 v[162:163], v[8:9], v[50:51]
	v_pk_fma_f32 v[160:161], v[2:3], v[42:43], v[160:161]
	v_pk_fma_f32 v[162:163], v[4:5], v[44:45], v[162:163]
	v_pk_fma_f32 v[160:161], v[10:11], v[54:55], v[160:161]
	v_pk_fma_f32 v[162:163], v[12:13], v[56:57], v[162:163]
	v_lshlrev_b32_e32 v156, 16, v58
	v_and_b32_e32 v157, 0xffff0000, v58
	v_lshlrev_b32_e32 v158, 16, v59
	v_and_b32_e32 v159, 0xffff0000, v59
	v_pk_mul_f32 v[204:205], v[160:161], v[156:157]
	v_pk_mul_f32 v[206:207], v[162:163], v[158:159]
	v_pk_mul_f32 v[156:157], v[204:205], v[204:205]
	v_pk_mul_f32 v[158:159], v[206:207], v[206:207]
	v_add_f32_e32 v156, v157, v156
	v_add_f32_e32 v158, v158, v159
	v_add_f32_e32 v187, v156, v158
	v_pk_mul_f32 v[152:153], v[6:7], v[54:55]
	v_pk_mul_f32 v[154:155], v[8:9], v[56:57]
	v_pk_fma_f32 v[152:153], v[2:3], v[48:49], v[152:153]
	v_pk_fma_f32 v[154:155], v[4:5], v[50:51], v[154:155]
	v_pk_fma_f32 v[152:153], v[10:11], v[60:61], v[152:153]
	v_pk_fma_f32 v[154:155], v[12:13], v[62:63], v[154:155]
	v_lshlrev_b32_e32 v148, 16, v64
	v_and_b32_e32 v149, 0xffff0000, v64
	v_lshlrev_b32_e32 v150, 16, v65
	v_and_b32_e32 v151, 0xffff0000, v65
	v_pk_mul_f32 v[208:209], v[152:153], v[148:149]
	v_pk_mul_f32 v[210:211], v[154:155], v[150:151]
	v_pk_mul_f32 v[148:149], v[208:209], v[208:209]
	v_pk_mul_f32 v[150:151], v[210:211], v[210:211]
	v_add_f32_e32 v148, v149, v148
	v_add_f32_e32 v150, v150, v151
	v_add_f32_e32 v188, v148, v150
	v_pk_mul_f32 v[160:161], v[6:7], v[60:61]
	v_pk_mul_f32 v[162:163], v[8:9], v[62:63]
	v_pk_fma_f32 v[160:161], v[2:3], v[54:55], v[160:161]
	v_pk_fma_f32 v[162:163], v[4:5], v[56:57], v[162:163]
	v_pk_fma_f32 v[160:161], v[10:11], v[66:67], v[160:161]
	v_pk_fma_f32 v[162:163], v[12:13], v[68:69], v[162:163]
	v_lshlrev_b32_e32 v156, 16, v70
	v_and_b32_e32 v157, 0xffff0000, v70
	v_lshlrev_b32_e32 v158, 16, v71
	v_and_b32_e32 v159, 0xffff0000, v71
	v_pk_mul_f32 v[212:213], v[160:161], v[156:157]
	v_pk_mul_f32 v[214:215], v[162:163], v[158:159]
	v_pk_mul_f32 v[156:157], v[212:213], v[212:213]
	v_pk_mul_f32 v[158:159], v[214:215], v[214:215]
	v_add_f32_e32 v156, v157, v156
	v_add_f32_e32 v158, v158, v159
	v_add_f32_e32 v189, v156, v158
	v_pk_mul_f32 v[152:153], v[6:7], v[66:67]
	v_pk_mul_f32 v[154:155], v[8:9], v[68:69]
	v_pk_fma_f32 v[152:153], v[2:3], v[60:61], v[152:153]
	v_pk_fma_f32 v[154:155], v[4:5], v[62:63], v[154:155]
	v_pk_fma_f32 v[152:153], v[10:11], v[72:73], v[152:153]
	v_pk_fma_f32 v[154:155], v[12:13], v[74:75], v[154:155]
	v_lshlrev_b32_e32 v148, 16, v76
	v_and_b32_e32 v149, 0xffff0000, v76
	v_lshlrev_b32_e32 v150, 16, v77
	v_and_b32_e32 v151, 0xffff0000, v77
	v_pk_mul_f32 v[216:217], v[152:153], v[148:149]
	v_pk_mul_f32 v[218:219], v[154:155], v[150:151]
	v_pk_mul_f32 v[148:149], v[216:217], v[216:217]
	v_pk_mul_f32 v[150:151], v[218:219], v[218:219]
	v_add_f32_e32 v148, v149, v148
	v_add_f32_e32 v150, v150, v151
	v_add_f32_e32 v190, v148, v150
	v_pk_mul_f32 v[160:161], v[6:7], v[72:73]
	v_pk_mul_f32 v[162:163], v[8:9], v[74:75]
	v_pk_fma_f32 v[160:161], v[2:3], v[66:67], v[160:161]
	v_pk_fma_f32 v[162:163], v[4:5], v[68:69], v[162:163]
	v_pk_fma_f32 v[160:161], v[10:11], v[78:79], v[160:161]
	v_pk_fma_f32 v[162:163], v[12:13], v[80:81], v[162:163]
	v_lshlrev_b32_e32 v156, 16, v82
	v_and_b32_e32 v157, 0xffff0000, v82
	v_lshlrev_b32_e32 v158, 16, v83
	v_and_b32_e32 v159, 0xffff0000, v83
	v_pk_mul_f32 v[224:225], v[160:161], v[156:157]
	v_pk_mul_f32 v[226:227], v[162:163], v[158:159]
	v_pk_mul_f32 v[156:157], v[224:225], v[224:225]
	v_pk_mul_f32 v[158:159], v[226:227], v[226:227]
	v_add_f32_e32 v156, v157, v156
	v_add_f32_e32 v158, v158, v159
	v_add_f32_e32 v191, v156, v158
	v_mov_b64_e32 v[18:19], v[72:73]
	v_mov_b64_e32 v[20:21], v[74:75]
	v_mov_b64_e32 v[22:23], v[78:79]
	v_mov_b64_e32 v[24:25], v[80:81]
	v_add_f32_dpp v184, v184, v184 quad_perm:[1,0,3,2] row_mask:0xf bank_mask:0xf
	v_add_f32_dpp v185, v185, v185 quad_perm:[1,0,3,2] row_mask:0xf bank_mask:0xf
	v_add_f32_dpp v186, v186, v186 quad_perm:[1,0,3,2] row_mask:0xf bank_mask:0xf
	v_add_f32_dpp v187, v187, v187 quad_perm:[1,0,3,2] row_mask:0xf bank_mask:0xf
	v_add_f32_dpp v188, v188, v188 quad_perm:[1,0,3,2] row_mask:0xf bank_mask:0xf
	v_add_f32_dpp v189, v189, v189 quad_perm:[1,0,3,2] row_mask:0xf bank_mask:0xf
	v_add_f32_dpp v190, v190, v190 quad_perm:[1,0,3,2] row_mask:0xf bank_mask:0xf
	v_add_f32_dpp v191, v191, v191 quad_perm:[1,0,3,2] row_mask:0xf bank_mask:0xf
	v_add_f32_dpp v184, v184, v184 quad_perm:[2,3,0,1] row_mask:0xf bank_mask:0xf
	v_add_f32_dpp v185, v185, v185 quad_perm:[2,3,0,1] row_mask:0xf bank_mask:0xf
	v_add_f32_dpp v186, v186, v186 quad_perm:[2,3,0,1] row_mask:0xf bank_mask:0xf
	v_add_f32_dpp v187, v187, v187 quad_perm:[2,3,0,1] row_mask:0xf bank_mask:0xf
	v_add_f32_dpp v188, v188, v188 quad_perm:[2,3,0,1] row_mask:0xf bank_mask:0xf
	v_add_f32_dpp v189, v189, v189 quad_perm:[2,3,0,1] row_mask:0xf bank_mask:0xf
	v_add_f32_dpp v190, v190, v190 quad_perm:[2,3,0,1] row_mask:0xf bank_mask:0xf
	v_add_f32_dpp v191, v191, v191 quad_perm:[2,3,0,1] row_mask:0xf bank_mask:0xf
	v_add_f32_dpp v184, v184, v184 row_half_mirror row_mask:0xf bank_mask:0xf
	v_add_f32_dpp v185, v185, v185 row_half_mirror row_mask:0xf bank_mask:0xf
	v_add_f32_dpp v186, v186, v186 row_half_mirror row_mask:0xf bank_mask:0xf
	v_add_f32_dpp v187, v187, v187 row_half_mirror row_mask:0xf bank_mask:0xf
	v_add_f32_dpp v188, v188, v188 row_half_mirror row_mask:0xf bank_mask:0xf
	v_add_f32_dpp v189, v189, v189 row_half_mirror row_mask:0xf bank_mask:0xf
	v_add_f32_dpp v190, v190, v190 row_half_mirror row_mask:0xf bank_mask:0xf
	v_add_f32_dpp v191, v191, v191 row_half_mirror row_mask:0xf bank_mask:0xf
	v_add_f32_dpp v184, v184, v184 row_mirror row_mask:0xf bank_mask:0xf
	v_add_f32_dpp v185, v185, v185 row_mirror row_mask:0xf bank_mask:0xf
	v_add_f32_dpp v186, v186, v186 row_mirror row_mask:0xf bank_mask:0xf
	v_add_f32_dpp v187, v187, v187 row_mirror row_mask:0xf bank_mask:0xf
	v_add_f32_dpp v188, v188, v188 row_mirror row_mask:0xf bank_mask:0xf
	v_add_f32_dpp v189, v189, v189 row_mirror row_mask:0xf bank_mask:0xf
	v_add_f32_dpp v190, v190, v190 row_mirror row_mask:0xf bank_mask:0xf
	v_add_f32_dpp v191, v191, v191 row_mirror row_mask:0xf bank_mask:0xf
	v_fmamk_f32 v184, v184, 0x3c800000, v173
	v_fmamk_f32 v185, v185, 0x3c800000, v173
	v_fmamk_f32 v186, v186, 0x3c800000, v173
	v_fmamk_f32 v187, v187, 0x3c800000, v173
	v_fmamk_f32 v188, v188, 0x3c800000, v173
	v_fmamk_f32 v189, v189, 0x3c800000, v173
	v_fmamk_f32 v190, v190, 0x3c800000, v173
	v_fmamk_f32 v191, v191, 0x3c800000, v173
	v_rsq_f32_e32 v184, v184
	v_rsq_f32_e32 v185, v185
	v_rsq_f32_e32 v186, v186
	v_rsq_f32_e32 v187, v187
	v_rsq_f32_e32 v188, v188
	v_rsq_f32_e32 v189, v189
	v_rsq_f32_e32 v190, v190
	v_rsq_f32_e32 v191, v191
	v_mul_f32_e32 v192, v192, v184
	v_mul_f32_e32 v193, v193, v184
	v_mul_f32_e32 v194, v194, v184
	v_mul_f32_e32 v195, v195, v184
	v_mul_f32_e32 v196, v196, v185
	v_mul_f32_e32 v197, v197, v185
	v_mul_f32_e32 v198, v198, v185
	v_mul_f32_e32 v199, v199, v185
	v_mul_f32_e32 v200, v200, v186
	v_mul_f32_e32 v201, v201, v186
	v_mul_f32_e32 v202, v202, v186
	v_mul_f32_e32 v203, v203, v186
	v_mul_f32_e32 v204, v204, v187
	v_mul_f32_e32 v205, v205, v187
	v_mul_f32_e32 v206, v206, v187
	v_mul_f32_e32 v207, v207, v187
	v_mul_f32_e32 v208, v208, v188
	v_mul_f32_e32 v209, v209, v188
	v_mul_f32_e32 v210, v210, v188
	v_mul_f32_e32 v211, v211, v188
	v_mul_f32_e32 v212, v212, v189
	v_mul_f32_e32 v213, v213, v189
	v_mul_f32_e32 v214, v214, v189
	v_mul_f32_e32 v215, v215, v189
	v_mul_f32_e32 v216, v216, v190
	v_mul_f32_e32 v217, v217, v190
	v_mul_f32_e32 v218, v218, v190
	v_mul_f32_e32 v219, v219, v190
	v_mul_f32_e32 v224, v224, v191
	v_mul_f32_e32 v225, v225, v191
	v_mul_f32_e32 v226, v226, v191
	v_mul_f32_e32 v227, v227, v191
	v_pk_mul_f32 v[192:193], v[14:15], v[192:193]
	v_pk_mul_f32 v[194:195], v[16:17], v[194:195]
	v_pk_mul_f32 v[196:197], v[14:15], v[196:197]
	v_pk_mul_f32 v[198:199], v[16:17], v[198:199]
	v_pk_mul_f32 v[200:201], v[14:15], v[200:201]
	v_pk_mul_f32 v[202:203], v[16:17], v[202:203]
	v_pk_mul_f32 v[204:205], v[14:15], v[204:205]
	v_pk_mul_f32 v[206:207], v[16:17], v[206:207]
	v_pk_mul_f32 v[208:209], v[14:15], v[208:209]
	v_pk_mul_f32 v[210:211], v[16:17], v[210:211]
	v_pk_mul_f32 v[212:213], v[14:15], v[212:213]
	v_pk_mul_f32 v[214:215], v[16:17], v[214:215]
	v_pk_mul_f32 v[216:217], v[14:15], v[216:217]
	v_pk_mul_f32 v[218:219], v[16:17], v[218:219]
	v_pk_mul_f32 v[224:225], v[14:15], v[224:225]
	v_pk_mul_f32 v[226:227], v[16:17], v[226:227]
	v_cvt_pk_bf16_f32 v192, v192, v193
	v_cvt_pk_bf16_f32 v193, v194, v195
	v_cvt_pk_bf16_f32 v196, v196, v197
	v_cvt_pk_bf16_f32 v197, v198, v199
	v_cvt_pk_bf16_f32 v200, v200, v201
	v_cvt_pk_bf16_f32 v201, v202, v203
	v_cvt_pk_bf16_f32 v204, v204, v205
	v_cvt_pk_bf16_f32 v205, v206, v207
	v_cvt_pk_bf16_f32 v208, v208, v209
	v_cvt_pk_bf16_f32 v209, v210, v211
	v_cvt_pk_bf16_f32 v212, v212, v213
	v_cvt_pk_bf16_f32 v213, v214, v215
	v_cvt_pk_bf16_f32 v216, v216, v217
	v_cvt_pk_bf16_f32 v217, v218, v219
	v_cvt_pk_bf16_f32 v224, v224, v225
	v_cvt_pk_bf16_f32 v225, v226, v227
	global_store_dwordx2 v0, v[192:193], s[2:3] offset:1536
	s_add_u32 s2, s2, 0x800
	s_addc_u32 s3, s3, 0
	global_store_dwordx2 v0, v[196:197], s[2:3] offset:1536
	s_add_u32 s2, s2, 0x800
	s_addc_u32 s3, s3, 0
	global_store_dwordx2 v0, v[200:201], s[2:3] offset:1536
	s_add_u32 s2, s2, 0x800
	s_addc_u32 s3, s3, 0
	global_store_dwordx2 v0, v[204:205], s[2:3] offset:1536
	s_add_u32 s2, s2, 0x800
	s_addc_u32 s3, s3, 0
	global_store_dwordx2 v0, v[208:209], s[2:3] offset:1536
	s_add_u32 s2, s2, 0x800
	s_addc_u32 s3, s3, 0
	global_store_dwordx2 v0, v[212:213], s[2:3] offset:1536
	s_add_u32 s2, s2, 0x800
	s_addc_u32 s3, s3, 0
	global_store_dwordx2 v0, v[216:217], s[2:3] offset:1536
	s_add_u32 s2, s2, 0x800
	s_addc_u32 s3, s3, 0
	global_store_dwordx2 v0, v[224:225], s[2:3] offset:1536
	s_add_u32 s2, s2, 0x800
	s_addc_u32 s3, s3, 0
	s_waitcnt vmcnt(8)
	v_lshlrev_b32_e32 v148, 16, v84
	v_and_b32_e32 v149, 0xffff0000, v84
	v_lshlrev_b32_e32 v150, 16, v86
	v_and_b32_e32 v151, 0xffff0000, v86
	v_lshlrev_b32_e32 v152, 16, v85
	v_and_b32_e32 v153, 0xffff0000, v85
	v_lshlrev_b32_e32 v154, 16, v87
	v_and_b32_e32 v155, 0xffff0000, v87
	v_pk_mul_f32 v[84:85], v[148:149], v[150:151]
	v_pk_mul_f32 v[86:87], v[152:153], v[154:155]
	v_lshlrev_b32_e32 v156, 16, v90
	v_and_b32_e32 v157, 0xffff0000, v90
	v_lshlrev_b32_e32 v158, 16, v92
	v_and_b32_e32 v159, 0xffff0000, v92
	v_lshlrev_b32_e32 v160, 16, v91
	v_and_b32_e32 v161, 0xffff0000, v91
	v_lshlrev_b32_e32 v162, 16, v93
	v_and_b32_e32 v163, 0xffff0000, v93
	v_pk_mul_f32 v[90:91], v[156:157], v[158:159]
	v_pk_mul_f32 v[92:93], v[160:161], v[162:163]
	v_lshlrev_b32_e32 v148, 16, v96
	v_and_b32_e32 v149, 0xffff0000, v96
	v_lshlrev_b32_e32 v150, 16, v98
	v_and_b32_e32 v151, 0xffff0000, v98
	v_lshlrev_b32_e32 v152, 16, v97
	v_and_b32_e32 v153, 0xffff0000, v97
	v_lshlrev_b32_e32 v154, 16, v99
	v_and_b32_e32 v155, 0xffff0000, v99
	v_pk_mul_f32 v[96:97], v[148:149], v[150:151]
	v_pk_mul_f32 v[98:99], v[152:153], v[154:155]
	v_lshlrev_b32_e32 v156, 16, v102
	v_and_b32_e32 v157, 0xffff0000, v102
	v_lshlrev_b32_e32 v158, 16, v104
	v_and_b32_e32 v159, 0xffff0000, v104
	v_lshlrev_b32_e32 v160, 16, v103
	v_and_b32_e32 v161, 0xffff0000, v103
	v_lshlrev_b32_e32 v162, 16, v105
	v_and_b32_e32 v163, 0xffff0000, v105
	v_pk_mul_f32 v[102:103], v[156:157], v[158:159]
	v_pk_mul_f32 v[104:105], v[160:161], v[162:163]
	v_lshlrev_b32_e32 v148, 16, v108
	v_and_b32_e32 v149, 0xffff0000, v108
	v_lshlrev_b32_e32 v150, 16, v110
	v_and_b32_e32 v151, 0xffff0000, v110
	v_lshlrev_b32_e32 v152, 16, v109
	v_and_b32_e32 v153, 0xffff0000, v109
	v_lshlrev_b32_e32 v154, 16, v111
	v_and_b32_e32 v155, 0xffff0000, v111
	v_pk_mul_f32 v[108:109], v[148:149], v[150:151]
	v_pk_mul_f32 v[110:111], v[152:153], v[154:155]
	v_lshlrev_b32_e32 v156, 16, v114
	v_and_b32_e32 v157, 0xffff0000, v114
	v_lshlrev_b32_e32 v158, 16, v116
	v_and_b32_e32 v159, 0xffff0000, v116
	v_lshlrev_b32_e32 v160, 16, v115
	v_and_b32_e32 v161, 0xffff0000, v115
	v_lshlrev_b32_e32 v162, 16, v117
	v_and_b32_e32 v163, 0xffff0000, v117
	v_pk_mul_f32 v[114:115], v[156:157], v[158:159]
	v_pk_mul_f32 v[116:117], v[160:161], v[162:163]
	v_lshlrev_b32_e32 v148, 16, v120
	v_and_b32_e32 v149, 0xffff0000, v120
	v_lshlrev_b32_e32 v150, 16, v122
	v_and_b32_e32 v151, 0xffff0000, v122
	v_lshlrev_b32_e32 v152, 16, v121
	v_and_b32_e32 v153, 0xffff0000, v121
	v_lshlrev_b32_e32 v154, 16, v123
	v_and_b32_e32 v155, 0xffff0000, v123
	v_pk_mul_f32 v[120:121], v[148:149], v[150:151]
	v_pk_mul_f32 v[122:123], v[152:153], v[154:155]
	v_lshlrev_b32_e32 v156, 16, v126
	v_and_b32_e32 v157, 0xffff0000, v126
	v_lshlrev_b32_e32 v158, 16, v128
	v_and_b32_e32 v159, 0xffff0000, v128
	v_lshlrev_b32_e32 v160, 16, v127
	v_and_b32_e32 v161, 0xffff0000, v127
	v_lshlrev_b32_e32 v162, 16, v129
	v_and_b32_e32 v163, 0xffff0000, v129
	v_pk_mul_f32 v[126:127], v[156:157], v[158:159]
	v_pk_mul_f32 v[128:129], v[160:161], v[162:163]
	v_pk_mul_f32 v[152:153], v[6:7], v[22:23]
	v_pk_mul_f32 v[154:155], v[8:9], v[24:25]
	v_pk_fma_f32 v[152:153], v[2:3], v[18:19], v[152:153]
	v_pk_fma_f32 v[154:155], v[4:5], v[20:21], v[154:155]
	v_pk_fma_f32 v[152:153], v[10:11], v[84:85], v[152:153]
	v_pk_fma_f32 v[154:155], v[12:13], v[86:87], v[154:155]
	v_lshlrev_b32_e32 v148, 16, v88
	v_and_b32_e32 v149, 0xffff0000, v88
	v_lshlrev_b32_e32 v150, 16, v89
	v_and_b32_e32 v151, 0xffff0000, v89
	v_pk_mul_f32 v[192:193], v[152:153], v[148:149]
	v_pk_mul_f32 v[194:195], v[154:155], v[150:151]
	v_pk_mul_f32 v[148:149], v[192:193], v[192:193]
	v_pk_mul_f32 v[150:151], v[194:195], v[194:195]
	v_add_f32_e32 v148, v149, v148
	v_add_f32_e32 v150, v150, v151
	v_add_f32_e32 v184, v148, v150
	v_pk_mul_f32 v[160:161], v[6:7], v[84:85]
	v_pk_mul_f32 v[162:163], v[8:9], v[86:87]
	v_pk_fma_f32 v[160:161], v[2:3], v[22:23], v[160:161]
	v_pk_fma_f32 v[162:163], v[4:5], v[24:25], v[162:163]
	v_pk_fma_f32 v[160:161], v[10:11], v[90:91], v[160:161]
	v_pk_fma_f32 v[162:163], v[12:13], v[92:93], v[162:163]
	v_lshlrev_b32_e32 v156, 16, v94
	v_and_b32_e32 v157, 0xffff0000, v94
	v_lshlrev_b32_e32 v158, 16, v95
	v_and_b32_e32 v159, 0xffff0000, v95
	v_pk_mul_f32 v[196:197], v[160:161], v[156:157]
	v_pk_mul_f32 v[198:199], v[162:163], v[158:159]
	v_pk_mul_f32 v[156:157], v[196:197], v[196:197]
	v_pk_mul_f32 v[158:159], v[198:199], v[198:199]
	v_add_f32_e32 v156, v157, v156
	v_add_f32_e32 v158, v158, v159
	v_add_f32_e32 v185, v156, v158
	v_pk_mul_f32 v[152:153], v[6:7], v[90:91]
	v_pk_mul_f32 v[154:155], v[8:9], v[92:93]
	v_pk_fma_f32 v[152:153], v[2:3], v[84:85], v[152:153]
	v_pk_fma_f32 v[154:155], v[4:5], v[86:87], v[154:155]
	v_pk_fma_f32 v[152:153], v[10:11], v[96:97], v[152:153]
	v_pk_fma_f32 v[154:155], v[12:13], v[98:99], v[154:155]
	v_lshlrev_b32_e32 v148, 16, v100
	v_and_b32_e32 v149, 0xffff0000, v100
	v_lshlrev_b32_e32 v150, 16, v101
	v_and_b32_e32 v151, 0xffff0000, v101
	v_pk_mul_f32 v[200:201], v[152:153], v[148:149]
	v_pk_mul_f32 v[202:203], v[154:155], v[150:151]
	v_pk_mul_f32 v[148:149], v[200:201], v[200:201]
	v_pk_mul_f32 v[150:151], v[202:203], v[202:203]
	v_add_f32_e32 v148, v149, v148
	v_add_f32_e32 v150, v150, v151
	v_add_f32_e32 v186, v148, v150
	v_pk_mul_f32 v[160:161], v[6:7], v[96:97]
	v_pk_mul_f32 v[162:163], v[8:9], v[98:99]
	v_pk_fma_f32 v[160:161], v[2:3], v[90:91], v[160:161]
	v_pk_fma_f32 v[162:163], v[4:5], v[92:93], v[162:163]
	v_pk_fma_f32 v[160:161], v[10:11], v[102:103], v[160:161]
	v_pk_fma_f32 v[162:163], v[12:13], v[104:105], v[162:163]
	v_lshlrev_b32_e32 v156, 16, v106
	v_and_b32_e32 v157, 0xffff0000, v106
	v_lshlrev_b32_e32 v158, 16, v107
	v_and_b32_e32 v159, 0xffff0000, v107
	v_pk_mul_f32 v[204:205], v[160:161], v[156:157]
	v_pk_mul_f32 v[206:207], v[162:163], v[158:159]
	v_pk_mul_f32 v[156:157], v[204:205], v[204:205]
	v_pk_mul_f32 v[158:159], v[206:207], v[206:207]
	v_add_f32_e32 v156, v157, v156
	v_add_f32_e32 v158, v158, v159
	v_add_f32_e32 v187, v156, v158
	v_pk_mul_f32 v[152:153], v[6:7], v[102:103]
	v_pk_mul_f32 v[154:155], v[8:9], v[104:105]
	v_pk_fma_f32 v[152:153], v[2:3], v[96:97], v[152:153]
	v_pk_fma_f32 v[154:155], v[4:5], v[98:99], v[154:155]
	v_pk_fma_f32 v[152:153], v[10:11], v[108:109], v[152:153]
	v_pk_fma_f32 v[154:155], v[12:13], v[110:111], v[154:155]
	v_lshlrev_b32_e32 v148, 16, v112
	v_and_b32_e32 v149, 0xffff0000, v112
	v_lshlrev_b32_e32 v150, 16, v113
	v_and_b32_e32 v151, 0xffff0000, v113
	v_pk_mul_f32 v[208:209], v[152:153], v[148:149]
	v_pk_mul_f32 v[210:211], v[154:155], v[150:151]
	v_pk_mul_f32 v[148:149], v[208:209], v[208:209]
	v_pk_mul_f32 v[150:151], v[210:211], v[210:211]
	v_add_f32_e32 v148, v149, v148
	v_add_f32_e32 v150, v150, v151
	v_add_f32_e32 v188, v148, v150
	v_pk_mul_f32 v[160:161], v[6:7], v[108:109]
	v_pk_mul_f32 v[162:163], v[8:9], v[110:111]
	v_pk_fma_f32 v[160:161], v[2:3], v[102:103], v[160:161]
	v_pk_fma_f32 v[162:163], v[4:5], v[104:105], v[162:163]
	v_pk_fma_f32 v[160:161], v[10:11], v[114:115], v[160:161]
	v_pk_fma_f32 v[162:163], v[12:13], v[116:117], v[162:163]
	v_lshlrev_b32_e32 v156, 16, v118
	v_and_b32_e32 v157, 0xffff0000, v118
	v_lshlrev_b32_e32 v158, 16, v119
	v_and_b32_e32 v159, 0xffff0000, v119
	v_pk_mul_f32 v[212:213], v[160:161], v[156:157]
	v_pk_mul_f32 v[214:215], v[162:163], v[158:159]
	v_pk_mul_f32 v[156:157], v[212:213], v[212:213]
	v_pk_mul_f32 v[158:159], v[214:215], v[214:215]
	v_add_f32_e32 v156, v157, v156
	v_add_f32_e32 v158, v158, v159
	v_add_f32_e32 v189, v156, v158
	v_pk_mul_f32 v[152:153], v[6:7], v[114:115]
	v_pk_mul_f32 v[154:155], v[8:9], v[116:117]
	v_pk_fma_f32 v[152:153], v[2:3], v[108:109], v[152:153]
	v_pk_fma_f32 v[154:155], v[4:5], v[110:111], v[154:155]
	v_pk_fma_f32 v[152:153], v[10:11], v[120:121], v[152:153]
	v_pk_fma_f32 v[154:155], v[12:13], v[122:123], v[154:155]
	v_lshlrev_b32_e32 v148, 16, v124
	v_and_b32_e32 v149, 0xffff0000, v124
	v_lshlrev_b32_e32 v150, 16, v125
	v_and_b32_e32 v151, 0xffff0000, v125
	v_pk_mul_f32 v[216:217], v[152:153], v[148:149]
	v_pk_mul_f32 v[218:219], v[154:155], v[150:151]
	v_pk_mul_f32 v[148:149], v[216:217], v[216:217]
	v_pk_mul_f32 v[150:151], v[218:219], v[218:219]
	v_add_f32_e32 v148, v149, v148
	v_add_f32_e32 v150, v150, v151
	v_add_f32_e32 v190, v148, v150
	v_pk_mul_f32 v[160:161], v[6:7], v[120:121]
	v_pk_mul_f32 v[162:163], v[8:9], v[122:123]
	v_pk_fma_f32 v[160:161], v[2:3], v[114:115], v[160:161]
	v_pk_fma_f32 v[162:163], v[4:5], v[116:117], v[162:163]
	v_pk_fma_f32 v[160:161], v[10:11], v[126:127], v[160:161]
	v_pk_fma_f32 v[162:163], v[12:13], v[128:129], v[162:163]
	v_lshlrev_b32_e32 v156, 16, v130
	v_and_b32_e32 v157, 0xffff0000, v130
	v_lshlrev_b32_e32 v158, 16, v131
	v_and_b32_e32 v159, 0xffff0000, v131
	v_pk_mul_f32 v[224:225], v[160:161], v[156:157]
	v_pk_mul_f32 v[226:227], v[162:163], v[158:159]
	v_pk_mul_f32 v[156:157], v[224:225], v[224:225]
	v_pk_mul_f32 v[158:159], v[226:227], v[226:227]
	v_add_f32_e32 v156, v157, v156
	v_add_f32_e32 v158, v158, v159
	v_add_f32_e32 v191, v156, v158
	v_add_f32_dpp v184, v184, v184 quad_perm:[1,0,3,2] row_mask:0xf bank_mask:0xf
	v_add_f32_dpp v185, v185, v185 quad_perm:[1,0,3,2] row_mask:0xf bank_mask:0xf
	v_add_f32_dpp v186, v186, v186 quad_perm:[1,0,3,2] row_mask:0xf bank_mask:0xf
	v_add_f32_dpp v187, v187, v187 quad_perm:[1,0,3,2] row_mask:0xf bank_mask:0xf
	v_add_f32_dpp v188, v188, v188 quad_perm:[1,0,3,2] row_mask:0xf bank_mask:0xf
	v_add_f32_dpp v189, v189, v189 quad_perm:[1,0,3,2] row_mask:0xf bank_mask:0xf
	v_add_f32_dpp v190, v190, v190 quad_perm:[1,0,3,2] row_mask:0xf bank_mask:0xf
	v_add_f32_dpp v191, v191, v191 quad_perm:[1,0,3,2] row_mask:0xf bank_mask:0xf
	v_add_f32_dpp v184, v184, v184 quad_perm:[2,3,0,1] row_mask:0xf bank_mask:0xf
	v_add_f32_dpp v185, v185, v185 quad_perm:[2,3,0,1] row_mask:0xf bank_mask:0xf
	v_add_f32_dpp v186, v186, v186 quad_perm:[2,3,0,1] row_mask:0xf bank_mask:0xf
	v_add_f32_dpp v187, v187, v187 quad_perm:[2,3,0,1] row_mask:0xf bank_mask:0xf
	v_add_f32_dpp v188, v188, v188 quad_perm:[2,3,0,1] row_mask:0xf bank_mask:0xf
	v_add_f32_dpp v189, v189, v189 quad_perm:[2,3,0,1] row_mask:0xf bank_mask:0xf
	v_add_f32_dpp v190, v190, v190 quad_perm:[2,3,0,1] row_mask:0xf bank_mask:0xf
	v_add_f32_dpp v191, v191, v191 quad_perm:[2,3,0,1] row_mask:0xf bank_mask:0xf
	v_add_f32_dpp v184, v184, v184 row_half_mirror row_mask:0xf bank_mask:0xf
	v_add_f32_dpp v185, v185, v185 row_half_mirror row_mask:0xf bank_mask:0xf
	v_add_f32_dpp v186, v186, v186 row_half_mirror row_mask:0xf bank_mask:0xf
	v_add_f32_dpp v187, v187, v187 row_half_mirror row_mask:0xf bank_mask:0xf
	v_add_f32_dpp v188, v188, v188 row_half_mirror row_mask:0xf bank_mask:0xf
	v_add_f32_dpp v189, v189, v189 row_half_mirror row_mask:0xf bank_mask:0xf
	v_add_f32_dpp v190, v190, v190 row_half_mirror row_mask:0xf bank_mask:0xf
	v_add_f32_dpp v191, v191, v191 row_half_mirror row_mask:0xf bank_mask:0xf
	v_add_f32_dpp v184, v184, v184 row_mirror row_mask:0xf bank_mask:0xf
	v_add_f32_dpp v185, v185, v185 row_mirror row_mask:0xf bank_mask:0xf
	v_add_f32_dpp v186, v186, v186 row_mirror row_mask:0xf bank_mask:0xf
	v_add_f32_dpp v187, v187, v187 row_mirror row_mask:0xf bank_mask:0xf
	v_add_f32_dpp v188, v188, v188 row_mirror row_mask:0xf bank_mask:0xf
	v_add_f32_dpp v189, v189, v189 row_mirror row_mask:0xf bank_mask:0xf
	v_add_f32_dpp v190, v190, v190 row_mirror row_mask:0xf bank_mask:0xf
	v_add_f32_dpp v191, v191, v191 row_mirror row_mask:0xf bank_mask:0xf
	v_fmamk_f32 v184, v184, 0x3c800000, v173
	v_fmamk_f32 v185, v185, 0x3c800000, v173
	v_fmamk_f32 v186, v186, 0x3c800000, v173
	v_fmamk_f32 v187, v187, 0x3c800000, v173
	v_fmamk_f32 v188, v188, 0x3c800000, v173
	v_fmamk_f32 v189, v189, 0x3c800000, v173
	v_fmamk_f32 v190, v190, 0x3c800000, v173
	v_fmamk_f32 v191, v191, 0x3c800000, v173
	v_rsq_f32_e32 v184, v184
	v_rsq_f32_e32 v185, v185
	v_rsq_f32_e32 v186, v186
	v_rsq_f32_e32 v187, v187
	v_rsq_f32_e32 v188, v188
	v_rsq_f32_e32 v189, v189
	v_rsq_f32_e32 v190, v190
	v_rsq_f32_e32 v191, v191
	v_mul_f32_e32 v192, v192, v184
	v_mul_f32_e32 v193, v193, v184
	v_mul_f32_e32 v194, v194, v184
	v_mul_f32_e32 v195, v195, v184
	v_mul_f32_e32 v196, v196, v185
	v_mul_f32_e32 v197, v197, v185
	v_mul_f32_e32 v198, v198, v185
	v_mul_f32_e32 v199, v199, v185
	v_mul_f32_e32 v200, v200, v186
	v_mul_f32_e32 v201, v201, v186
	v_mul_f32_e32 v202, v202, v186
	v_mul_f32_e32 v203, v203, v186
	v_mul_f32_e32 v204, v204, v187
	v_mul_f32_e32 v205, v205, v187
	v_mul_f32_e32 v206, v206, v187
	v_mul_f32_e32 v207, v207, v187
	v_mul_f32_e32 v208, v208, v188
	v_mul_f32_e32 v209, v209, v188
	v_mul_f32_e32 v210, v210, v188
	v_mul_f32_e32 v211, v211, v188
	v_mul_f32_e32 v212, v212, v189
	v_mul_f32_e32 v213, v213, v189
	v_mul_f32_e32 v214, v214, v189
	v_mul_f32_e32 v215, v215, v189
	v_mul_f32_e32 v216, v216, v190
	v_mul_f32_e32 v217, v217, v190
	v_mul_f32_e32 v218, v218, v190
	v_mul_f32_e32 v219, v219, v190
	v_mul_f32_e32 v224, v224, v191
	v_mul_f32_e32 v225, v225, v191
	v_mul_f32_e32 v226, v226, v191
	v_mul_f32_e32 v227, v227, v191
	v_pk_mul_f32 v[192:193], v[14:15], v[192:193]
	v_pk_mul_f32 v[194:195], v[16:17], v[194:195]
	v_pk_mul_f32 v[196:197], v[14:15], v[196:197]
	v_pk_mul_f32 v[198:199], v[16:17], v[198:199]
	v_pk_mul_f32 v[200:201], v[14:15], v[200:201]
	v_pk_mul_f32 v[202:203], v[16:17], v[202:203]
	v_pk_mul_f32 v[204:205], v[14:15], v[204:205]
	v_pk_mul_f32 v[206:207], v[16:17], v[206:207]
	v_pk_mul_f32 v[208:209], v[14:15], v[208:209]
	v_pk_mul_f32 v[210:211], v[16:17], v[210:211]
	v_pk_mul_f32 v[212:213], v[14:15], v[212:213]
	v_pk_mul_f32 v[214:215], v[16:17], v[214:215]
	v_pk_mul_f32 v[216:217], v[14:15], v[216:217]
	v_pk_mul_f32 v[218:219], v[16:17], v[218:219]
	v_pk_mul_f32 v[224:225], v[14:15], v[224:225]
	v_pk_mul_f32 v[226:227], v[16:17], v[226:227]
	v_cvt_pk_bf16_f32 v192, v192, v193
	v_cvt_pk_bf16_f32 v193, v194, v195
	v_cvt_pk_bf16_f32 v196, v196, v197
	v_cvt_pk_bf16_f32 v197, v198, v199
	v_cvt_pk_bf16_f32 v200, v200, v201
	v_cvt_pk_bf16_f32 v201, v202, v203
	v_cvt_pk_bf16_f32 v204, v204, v205
	v_cvt_pk_bf16_f32 v205, v206, v207
	v_cvt_pk_bf16_f32 v208, v208, v209
	v_cvt_pk_bf16_f32 v209, v210, v211
	v_cvt_pk_bf16_f32 v212, v212, v213
	v_cvt_pk_bf16_f32 v213, v214, v215
	v_cvt_pk_bf16_f32 v216, v216, v217
	v_cvt_pk_bf16_f32 v217, v218, v219
	v_cvt_pk_bf16_f32 v224, v224, v225
	v_cvt_pk_bf16_f32 v225, v226, v227
	global_store_dwordx2 v0, v[192:193], s[2:3] offset:1536
	s_add_u32 s2, s2, 0x800
	s_addc_u32 s3, s3, 0
	global_store_dwordx2 v0, v[196:197], s[2:3] offset:1536
	s_add_u32 s2, s2, 0x800
	s_addc_u32 s3, s3, 0
	global_store_dwordx2 v0, v[200:201], s[2:3] offset:1536
	s_add_u32 s2, s2, 0x800
	s_addc_u32 s3, s3, 0
	global_store_dwordx2 v0, v[204:205], s[2:3] offset:1536
	s_add_u32 s2, s2, 0x800
	s_addc_u32 s3, s3, 0
	global_store_dwordx2 v0, v[208:209], s[2:3] offset:1536
	s_add_u32 s2, s2, 0x800
	s_addc_u32 s3, s3, 0
	global_store_dwordx2 v0, v[212:213], s[2:3] offset:1536
	s_add_u32 s2, s2, 0x800
	s_addc_u32 s3, s3, 0
	global_store_dwordx2 v0, v[216:217], s[2:3] offset:1536
	s_add_u32 s2, s2, 0x800
	s_addc_u32 s3, s3, 0
	global_store_dwordx2 v0, v[224:225], s[2:3] offset:1536
	s_add_u32 s2, s2, 0x800
	s_addc_u32 s3, s3, 0
	s_branch .LBB0_114

.LBB0_272:
	v_add_u32_e32 v4, v3, v82
	v_ashrrev_i32_e32 v4, 1, v4
	v_lshl_add_u32 v5, v4, 8, 0
	ds_read_b32 v5, v5 offset:252
	s_waitcnt lgkmcnt(0)
	v_sub_f32_e32 v5, v2, v5
	v_cmp_nge_f32_e64 vcc, v5, -v0
	v_add_u32_e32 v5, 1, v4
	s_nop 0
	v_cndmask_b32_e32 v3, v4, v3, vcc
	v_cndmask_b32_e32 v82, v82, v5, vcc
	v_cmp_ge_i32_e32 vcc, v82, v3
	s_or_b64 s[2:3], vcc, s[2:3]
	s_andn2_b64 exec, exec, s[2:3]
	s_cbranch_execnz .LBB0_272
	s_or_b64 exec, exec, s[2:3]
	s_branch .LBB0_279
.Ltramp_569:
	s_branch .LBB0_569
.Ltramp_552:
	s_branch .LBB0_552
.Ltramp_568:
	s_branch .LBB0_568
.LBB0_274:
	v_ashrrev_i32_e32 v23, 31, v22
	v_lshl_add_u64 v[14:15], v[22:23], 2, s[10:11]
	flat_load_dwordx4 v[14:17], v[14:15]
	s_or_b64 exec, exec, s[20:21]
	s_and_saveexec_b64 s[10:11], vcc
	s_cbranch_execz .LBB0_262
